# GEMM loops: redundant post-barrier s_waitcnt lgkmcnt(0) at the head of each MFMA block deleted (24 sites; the wait before the barrier already drained LDS)
# baseline (speedup 1.0000x reference)
; #define PG8_STAGE(bufoff, gbase, voff) do { _Pragma("unroll") for (int _i = 0; _i < 2; ++_i) \
;         __builtin_amdgcn_global_load_lds((const unsigned*)((const char*)(gbase) + (voff)[_i]), (LAS unsigned*)(lds + (bufoff) + ldsw + _i * 8192), 16, 0, 0); } while (0)
; #define PG8_LDA(dst, b, h) do { _Pragma("unroll") for (int m = 0; m < 4; ++m) _Pragma("unroll") for (int k = 0; k < 2; ++k) dst[m][k] = *(const LAS bf16x8*)(lds + PG8_SA(b, h) + aoff + m * 2048 + k * 1024); } while (0)
; #define PG8_LDB(dst, b, h) do { _Pragma("unroll") for (int n = 0; n < 2; ++n) _Pragma("unroll") for (int k = 0; k < 2; ++k) dst[n][k] = *(const LAS bf16x8*)(lds + PG8_SB(b, h) + boff + n * 2048 + k * 1024); } while (0)
; #define PG8_MMA(ai, bj, At, Bt) do { __builtin_amdgcn_s_setprio(1); _Pragma("unroll") for (int m = 0; m < 4; ++m) _Pragma("unroll") for (int n = 0; n < 2; ++n) _Pragma("unroll") for (int k = 0; k < 2; ++k) \
;         acc[ai][bj][m][n] = __builtin_amdgcn_mfma_f32_16x16x32_bf16(Bt[n][k], At[m][k], acc[ai][bj][m][n], 0, 0, 0); __builtin_amdgcn_s_setprio(0); } while (0)
; #define PG8_WAIT_V(n) asm volatile("s_waitcnt vmcnt(" #n ")" ::: "memory")
; #define PG8_WAIT_L(n) asm volatile("s_waitcnt lgkmcnt(" #n ")" ::: "memory")
; #define PG8_BAR __builtin_amdgcn_s_barrier()
; template <class Epi, class Sched, bool ALIGN_EPI = false, bool SP2 = false>
; __device__ __forceinline__ void gemm_phase(LAS unsigned char* lds, const Gemm g, const Sched& S, const Epi& E) {
;     ...
;             const bool last = (t == nt - 2);
;             const char* a1 = cA + (size_t)(t + 1) * kstep;
;             const char* a2 = last ? nA : cA + (size_t)(t + 2) * kstep; const char* b2 = last ? nB : cB + (size_t)(t + 2) * kstep;
;             const char* a3 = a2 + kstep; const char* b3 = b2 + kstep;
;             if (last && has_next) S.a_ready(nxt);
;             if constexpr (SP2) {
;             PG8_LDB(B0, 0, 0); PG8_LDB(B1, 0, 1); PG8_SCHED; PG8_LDA(At, 0, 0); PG8_STAGE(PG8_SA(1, 1), a1 + hstepA, voffA);
;             PG8_WAIT_V(8); PG8_WAIT_L(0); PG8_BAR; PG8_MMA(0, 0, At, B0); PG8_MMA(0, 1, At, B1); PG8_BAR; PG8_SCHED;
;             PG8_LDA(At, 0, 1); PG8_STAGE(PG8_SB(0, 0), b2, voffB); PG8_STAGE(PG8_SB(0, 1), b2 + hstepB, voffB); PG8_STAGE(PG8_SA(0, 0), a2, voffA);
;             PG8_WAIT_V(8); PG8_WAIT_L(0); PG8_BAR; PG8_MMA(1, 0, At, B0); PG8_MMA(1, 1, At, B1); PG8_BAR; PG8_SCHED;
.LBB0_349:
	ds_read_b128 v[156:159], v149
	ds_read_b128 v[160:163], v149 offset:1024
	ds_read_b128 v[164:167], v149 offset:2048
	ds_read_b128 v[168:171], v149 offset:3072
	ds_read_b128 v[172:175], v150
	ds_read_b128 v[176:179], v150 offset:1024
	ds_read_b128 v[180:183], v150 offset:2048
	ds_read_b128 v[184:187], v150 offset:3072
	s_add_u32 s24, s22, 0xfff80080
	s_addc_u32 s25, s23, -1
	s_cmp_eq_u32 s58, 28
	s_cselect_b32 s27, s15, s25
	s_cselect_b32 s26, s47, s24
	s_cselect_b32 s25, s13, s55
	s_cselect_b32 s24, s50, s51
	v_lshl_add_u64 v[146:147], s[22:23], 0, v[138:139]
	s_add_i32 m0, s21, 0xc000
	ds_read_b128 v[188:191], v151
	ds_read_b128 v[192:195], v151 offset:1024
	ds_read_b128 v[196:199], v151 offset:2048
	ds_read_b128 v[200:203], v151 offset:3072
	ds_read_b128 v[204:207], v151 offset:4096
	ds_read_b128 v[208:211], v151 offset:5120
	ds_read_b128 v[212:215], v151 offset:6144
	ds_read_b128 v[216:219], v151 offset:7168
	global_load_lds_dwordx4 v[146:147], off
	v_lshl_add_u64 v[146:147], s[22:23], 0, v[140:141]
	s_add_i32 m0, s21, 0xe000
	s_nop 0
	global_load_lds_dwordx4 v[146:147], off
	s_waitcnt vmcnt(8)
	s_waitcnt lgkmcnt(0)
	s_barrier
	s_setprio 1
	v_mfma_f32_16x16x32_bf16 v[126:129], v[156:159], v[188:191], v[126:129]
	v_mfma_f32_16x16x32_bf16 v[122:125], v[164:167], v[188:191], v[122:125]
	v_mfma_f32_16x16x32_bf16 v[118:121], v[156:159], v[196:199], v[118:121]
	v_mfma_f32_16x16x32_bf16 v[110:113], v[164:167], v[196:199], v[110:113]
	v_mfma_f32_16x16x32_bf16 v[102:105], v[156:159], v[204:207], v[102:105]
	v_mfma_f32_16x16x32_bf16 v[94:97], v[164:167], v[204:207], v[94:97]
	v_mfma_f32_16x16x32_bf16 v[86:89], v[156:159], v[212:215], v[86:89]
	v_mfma_f32_16x16x32_bf16 v[78:81], v[164:167], v[212:215], v[78:81]
	v_mfma_f32_16x16x32_bf16 v[126:129], v[160:163], v[192:195], v[126:129]
	v_mfma_f32_16x16x32_bf16 v[122:125], v[168:171], v[192:195], v[122:125]
	v_mfma_f32_16x16x32_bf16 v[118:121], v[160:163], v[200:203], v[118:121]
	v_mfma_f32_16x16x32_bf16 v[110:113], v[168:171], v[200:203], v[110:113]
	v_mfma_f32_16x16x32_bf16 v[102:105], v[160:163], v[208:211], v[102:105]
	v_mfma_f32_16x16x32_bf16 v[94:97], v[168:171], v[208:211], v[94:97]
	v_mfma_f32_16x16x32_bf16 v[86:89], v[160:163], v[216:219], v[86:89]
	v_mfma_f32_16x16x32_bf16 v[78:81], v[168:171], v[216:219], v[78:81]
	s_setprio 0
	s_setprio 1
	v_mfma_f32_16x16x32_bf16 v[114:117], v[172:175], v[188:191], v[114:117]
	v_mfma_f32_16x16x32_bf16 v[106:109], v[180:183], v[188:191], v[106:109]
	v_mfma_f32_16x16x32_bf16 v[98:101], v[172:175], v[196:199], v[98:101]
	v_mfma_f32_16x16x32_bf16 v[90:93], v[180:183], v[196:199], v[90:93]
	v_mfma_f32_16x16x32_bf16 v[82:85], v[172:175], v[204:207], v[82:85]
	v_mfma_f32_16x16x32_bf16 v[74:77], v[180:183], v[204:207], v[74:77]
	v_mfma_f32_16x16x32_bf16 v[70:73], v[172:175], v[212:215], v[70:73]
	v_mfma_f32_16x16x32_bf16 v[66:69], v[180:183], v[212:215], v[66:69]
	v_mfma_f32_16x16x32_bf16 v[114:117], v[176:179], v[192:195], v[114:117]
	v_mfma_f32_16x16x32_bf16 v[106:109], v[184:187], v[192:195], v[106:109]
	v_mfma_f32_16x16x32_bf16 v[98:101], v[176:179], v[200:203], v[98:101]
	v_mfma_f32_16x16x32_bf16 v[90:93], v[184:187], v[200:203], v[90:93]
	v_mfma_f32_16x16x32_bf16 v[82:85], v[176:179], v[208:211], v[82:85]
	v_mfma_f32_16x16x32_bf16 v[74:77], v[184:187], v[208:211], v[74:77]
	v_mfma_f32_16x16x32_bf16 v[70:73], v[176:179], v[216:219], v[70:73]
	v_mfma_f32_16x16x32_bf16 v[66:69], v[184:187], v[216:219], v[66:69]
	s_setprio 0
	s_barrier
	s_add_i32 s59, s40, s28
	v_lshl_add_u64 v[146:147], s[24:25], 0, v[134:135]
	s_mov_b32 m0, s59
	ds_read_b128 v[188:191], v151 offset:16384
	ds_read_b128 v[192:195], v151 offset:17408
	ds_read_b128 v[196:199], v151 offset:18432
	ds_read_b128 v[200:203], v151 offset:19456
	ds_read_b128 v[204:207], v151 offset:20480
	ds_read_b128 v[208:211], v151 offset:21504
	ds_read_b128 v[212:215], v151 offset:22528
	ds_read_b128 v[216:219], v151 offset:23552
	global_load_lds_dwordx4 v[146:147], off
	s_add_i32 m0, s59, 0x2000
	s_add_u32 s60, s24, 0x80000
	v_lshl_add_u64 v[220:221], s[24:25], 0, v[130:131]
	s_addc_u32 s61, s25, 0
	s_add_i32 s59, s41, s28
	global_load_lds_dwordx4 v[220:221], off
	v_lshl_add_u64 v[222:223], s[60:61], 0, v[134:135]
	s_mov_b32 m0, s59
	v_lshl_add_u64 v[224:225], s[26:27], 0, v[132:133]
	global_load_lds_dwordx4 v[222:223], off
	v_lshl_add_u64 v[222:223], s[60:61], 0, v[130:131]
	s_add_i32 m0, s59, 0x2000
	s_nop 0
	global_load_lds_dwordx4 v[222:223], off
	v_lshl_add_u64 v[222:223], s[26:27], 0, v[136:137]
	s_mov_b32 m0, s21
	s_nop 0
	global_load_lds_dwordx4 v[222:223], off
	s_mov_b32 m0, s31
	s_nop 0
	global_load_lds_dwordx4 v[224:225], off
	s_waitcnt vmcnt(8)
	s_waitcnt lgkmcnt(0)
	s_barrier
; #define PG8_STAGE(bufoff, gbase, voff) do { _Pragma("unroll") for (int _i = 0; _i < 2; ++_i) \
;         __builtin_amdgcn_global_load_lds((const unsigned*)((const char*)(gbase) + (voff)[_i]), (LAS unsigned*)(lds + (bufoff) + ldsw + _i * 8192), 16, 0, 0); } while (0)
; #define PG8_LDA(dst, b, h) do { _Pragma("unroll") for (int m = 0; m < 4; ++m) _Pragma("unroll") for (int k = 0; k < 2; ++k) dst[m][k] = *(const LAS bf16x8*)(lds + PG8_SA(b, h) + aoff + m * 2048 + k * 1024); } while (0)
; #define PG8_LDB(dst, b, h) do { _Pragma("unroll") for (int n = 0; n < 2; ++n) _Pragma("unroll") for (int k = 0; k < 2; ++k) dst[n][k] = *(const LAS bf16x8*)(lds + PG8_SB(b, h) + boff + n * 2048 + k * 1024); } while (0)
; #define PG8_MMA(ai, bj, At, Bt) do { __builtin_amdgcn_s_setprio(1); _Pragma("unroll") for (int m = 0; m < 4; ++m) _Pragma("unroll") for (int n = 0; n < 2; ++n) _Pragma("unroll") for (int k = 0; k < 2; ++k) \
;         acc[ai][bj][m][n] = __builtin_amdgcn_mfma_f32_16x16x32_bf16(Bt[n][k], At[m][k], acc[ai][bj][m][n], 0, 0, 0); __builtin_amdgcn_s_setprio(0); } while (0)
; #define PG8_WAIT_V(n) asm volatile("s_waitcnt vmcnt(" #n ")" ::: "memory")
; #define PG8_WAIT_L(n) asm volatile("s_waitcnt lgkmcnt(" #n ")" ::: "memory")
; #define PG8_BAR __builtin_amdgcn_s_barrier()
; #define PG8_SCHED __builtin_amdgcn_sched_barrier(0)
; template <class Epi, class Sched, bool ALIGN_EPI = false, bool SP2 = false>
; __device__ __forceinline__ void gemm_phase(LAS unsigned char* lds, const Gemm g, const Sched& S, const Epi& E) {
;     ...
;             PG8_WAIT_V(8); PG8_WAIT_L(0); PG8_BAR; PG8_MMA(1, 0, At, B0); PG8_MMA(1, 1, At, B1); PG8_BAR; PG8_SCHED;
;             PG8_LDB(B0, 1, 0); PG8_LDB(B1, 1, 1); PG8_SCHED; PG8_LDA(At, 1, 0); PG8_STAGE(PG8_SA(0, 1), a2 + hstepA, voffA);
;             PG8_WAIT_V(8); PG8_WAIT_L(0); PG8_BAR; PG8_MMA(0, 0, At, B0); PG8_MMA(0, 1, At, B1); PG8_BAR; PG8_SCHED;
	s_setprio 1
	v_mfma_f32_16x16x32_bf16 v[62:65], v[156:159], v[188:191], v[62:65]
	v_mfma_f32_16x16x32_bf16 v[58:61], v[164:167], v[188:191], v[58:61]
	v_mfma_f32_16x16x32_bf16 v[54:57], v[156:159], v[196:199], v[54:57]
	v_mfma_f32_16x16x32_bf16 v[46:49], v[164:167], v[196:199], v[46:49]
	v_mfma_f32_16x16x32_bf16 v[38:41], v[156:159], v[204:207], v[38:41]
	v_mfma_f32_16x16x32_bf16 v[30:33], v[164:167], v[204:207], v[30:33]
	v_mfma_f32_16x16x32_bf16 v[22:25], v[156:159], v[212:215], v[22:25]
	v_mfma_f32_16x16x32_bf16 v[14:17], v[164:167], v[212:215], v[14:17]
	v_mfma_f32_16x16x32_bf16 v[62:65], v[160:163], v[192:195], v[62:65]
	v_mfma_f32_16x16x32_bf16 v[58:61], v[168:171], v[192:195], v[58:61]
	v_mfma_f32_16x16x32_bf16 v[54:57], v[160:163], v[200:203], v[54:57]
	v_mfma_f32_16x16x32_bf16 v[46:49], v[168:171], v[200:203], v[46:49]
	v_mfma_f32_16x16x32_bf16 v[38:41], v[160:163], v[208:211], v[38:41]
	v_mfma_f32_16x16x32_bf16 v[30:33], v[168:171], v[208:211], v[30:33]
	v_mfma_f32_16x16x32_bf16 v[22:25], v[160:163], v[216:219], v[22:25]
	v_mfma_f32_16x16x32_bf16 v[14:17], v[168:171], v[216:219], v[14:17]
	s_setprio 0
	s_setprio 1
	v_mfma_f32_16x16x32_bf16 v[50:53], v[172:175], v[188:191], v[50:53]
	v_mfma_f32_16x16x32_bf16 v[42:45], v[180:183], v[188:191], v[42:45]
	v_mfma_f32_16x16x32_bf16 v[34:37], v[172:175], v[196:199], v[34:37]
	v_mfma_f32_16x16x32_bf16 v[26:29], v[180:183], v[196:199], v[26:29]
	v_mfma_f32_16x16x32_bf16 v[18:21], v[172:175], v[204:207], v[18:21]
	v_mfma_f32_16x16x32_bf16 v[10:13], v[180:183], v[204:207], v[10:13]
	v_mfma_f32_16x16x32_bf16 v[6:9], v[172:175], v[212:215], v[6:9]
	v_mfma_f32_16x16x32_bf16 v[2:5], v[180:183], v[212:215], v[2:5]
	v_mfma_f32_16x16x32_bf16 v[50:53], v[176:179], v[192:195], v[50:53]
	v_mfma_f32_16x16x32_bf16 v[42:45], v[184:187], v[192:195], v[42:45]
	v_mfma_f32_16x16x32_bf16 v[34:37], v[176:179], v[200:203], v[34:37]
	v_mfma_f32_16x16x32_bf16 v[26:29], v[184:187], v[200:203], v[26:29]
	v_mfma_f32_16x16x32_bf16 v[18:21], v[176:179], v[208:211], v[18:21]
	v_mfma_f32_16x16x32_bf16 v[10:13], v[184:187], v[208:211], v[10:13]
	v_mfma_f32_16x16x32_bf16 v[6:9], v[176:179], v[216:219], v[6:9]
	v_mfma_f32_16x16x32_bf16 v[2:5], v[184:187], v[216:219], v[2:5]
	s_setprio 0
	s_barrier
	ds_read_b128 v[156:159], v153
	ds_read_b128 v[160:163], v153 offset:1024
	ds_read_b128 v[164:167], v153 offset:2048
	ds_read_b128 v[168:171], v153 offset:3072
	ds_read_b128 v[172:175], v154
	ds_read_b128 v[176:179], v154 offset:1024
	ds_read_b128 v[180:183], v154 offset:2048
	ds_read_b128 v[184:187], v154 offset:3072
	s_add_u32 s26, s26, 0x80000
	s_addc_u32 s27, s27, 0
	s_mov_b32 m0, s33
	v_lshl_add_u64 v[226:227], s[26:27], 0, v[136:137]
	ds_read_b128 v[188:191], v151 offset:32768
	ds_read_b128 v[192:195], v151 offset:33792
	ds_read_b128 v[196:199], v151 offset:34816
	ds_read_b128 v[200:203], v151 offset:35840
	ds_read_b128 v[204:207], v151 offset:36864
	ds_read_b128 v[208:211], v151 offset:37888
	ds_read_b128 v[212:215], v151 offset:38912
	ds_read_b128 v[216:219], v151 offset:39936
	global_load_lds_dwordx4 v[226:227], off
	v_lshl_add_u64 v[226:227], s[26:27], 0, v[132:133]
	s_mov_b32 m0, s34
	s_nop 0
	global_load_lds_dwordx4 v[226:227], off
	s_waitcnt vmcnt(8)
	s_waitcnt lgkmcnt(0)
	s_barrier
	s_setprio 1
	v_mfma_f32_16x16x32_bf16 v[126:129], v[156:159], v[188:191], v[126:129]
	v_mfma_f32_16x16x32_bf16 v[122:125], v[164:167], v[188:191], v[122:125]
	v_mfma_f32_16x16x32_bf16 v[118:121], v[156:159], v[196:199], v[118:121]
	v_mfma_f32_16x16x32_bf16 v[110:113], v[164:167], v[196:199], v[110:113]
	v_mfma_f32_16x16x32_bf16 v[102:105], v[156:159], v[204:207], v[102:105]
	v_mfma_f32_16x16x32_bf16 v[94:97], v[164:167], v[204:207], v[94:97]
	v_mfma_f32_16x16x32_bf16 v[86:89], v[156:159], v[212:215], v[86:89]
	v_mfma_f32_16x16x32_bf16 v[78:81], v[164:167], v[212:215], v[78:81]
	v_mfma_f32_16x16x32_bf16 v[126:129], v[160:163], v[192:195], v[126:129]
	v_mfma_f32_16x16x32_bf16 v[122:125], v[168:171], v[192:195], v[122:125]
	v_mfma_f32_16x16x32_bf16 v[118:121], v[160:163], v[200:203], v[118:121]
	v_mfma_f32_16x16x32_bf16 v[110:113], v[168:171], v[200:203], v[110:113]
	v_mfma_f32_16x16x32_bf16 v[102:105], v[160:163], v[208:211], v[102:105]
	v_mfma_f32_16x16x32_bf16 v[94:97], v[168:171], v[208:211], v[94:97]
	v_mfma_f32_16x16x32_bf16 v[86:89], v[160:163], v[216:219], v[86:89]
	v_mfma_f32_16x16x32_bf16 v[78:81], v[168:171], v[216:219], v[78:81]
	s_setprio 0
	s_setprio 1
	v_mfma_f32_16x16x32_bf16 v[114:117], v[172:175], v[188:191], v[114:117]
	v_mfma_f32_16x16x32_bf16 v[106:109], v[180:183], v[188:191], v[106:109]
	v_mfma_f32_16x16x32_bf16 v[98:101], v[172:175], v[196:199], v[98:101]
	v_mfma_f32_16x16x32_bf16 v[90:93], v[180:183], v[196:199], v[90:93]
	v_mfma_f32_16x16x32_bf16 v[82:85], v[172:175], v[204:207], v[82:85]
	v_mfma_f32_16x16x32_bf16 v[74:77], v[180:183], v[204:207], v[74:77]
	v_mfma_f32_16x16x32_bf16 v[70:73], v[172:175], v[212:215], v[70:73]
	v_mfma_f32_16x16x32_bf16 v[66:69], v[180:183], v[212:215], v[66:69]
	v_mfma_f32_16x16x32_bf16 v[114:117], v[176:179], v[192:195], v[114:117]
	v_mfma_f32_16x16x32_bf16 v[106:109], v[184:187], v[192:195], v[106:109]
	v_mfma_f32_16x16x32_bf16 v[98:101], v[176:179], v[200:203], v[98:101]
	v_mfma_f32_16x16x32_bf16 v[90:93], v[184:187], v[200:203], v[90:93]
	v_mfma_f32_16x16x32_bf16 v[82:85], v[176:179], v[208:211], v[82:85]
	v_mfma_f32_16x16x32_bf16 v[74:77], v[184:187], v[208:211], v[74:77]
	v_mfma_f32_16x16x32_bf16 v[70:73], v[176:179], v[216:219], v[70:73]
	v_mfma_f32_16x16x32_bf16 v[66:69], v[184:187], v[216:219], v[66:69]
	s_setprio 0
	s_barrier
; #define PG8_STAGE(bufoff, gbase, voff) do { _Pragma("unroll") for (int _i = 0; _i < 2; ++_i) \
;         __builtin_amdgcn_global_load_lds((const unsigned*)((const char*)(gbase) + (voff)[_i]), (LAS unsigned*)(lds + (bufoff) + ldsw + _i * 8192), 16, 0, 0); } while (0)
; #define PG8_LDA(dst, b, h) do { _Pragma("unroll") for (int m = 0; m < 4; ++m) _Pragma("unroll") for (int k = 0; k < 2; ++k) dst[m][k] = *(const LAS bf16x8*)(lds + PG8_SA(b, h) + aoff + m * 2048 + k * 1024); } while (0)
; #define PG8_MMA(ai, bj, At, Bt) do { __builtin_amdgcn_s_setprio(1); _Pragma("unroll") for (int m = 0; m < 4; ++m) _Pragma("unroll") for (int n = 0; n < 2; ++n) _Pragma("unroll") for (int k = 0; k < 2; ++k) \
;         acc[ai][bj][m][n] = __builtin_amdgcn_mfma_f32_16x16x32_bf16(Bt[n][k], At[m][k], acc[ai][bj][m][n], 0, 0, 0); __builtin_amdgcn_s_setprio(0); } while (0)
; #define PG8_WAIT_V(n) asm volatile("s_waitcnt vmcnt(" #n ")" ::: "memory")
; #define PG8_WAIT_L(n) asm volatile("s_waitcnt lgkmcnt(" #n ")" ::: "memory")
; #define PG8_BAR __builtin_amdgcn_s_barrier()
; #define PG8_SCHED __builtin_amdgcn_sched_barrier(0)
; template <class Epi, class Sched, bool ALIGN_EPI = false, bool SP2 = false>
; __device__ __forceinline__ void gemm_phase(LAS unsigned char* lds, const Gemm g, const Sched& S, const Epi& E) {
;     ...
;         for (int t = 0; t < nt; t += 2) {
;             const bool last = (t == nt - 2);
;     ...
;             PG8_LDA(At, 1, 1); PG8_STAGE(PG8_SB(1, 0), b3, voffB); PG8_STAGE(PG8_SB(1, 1), b3 + hstepB, voffB); PG8_STAGE(PG8_SA(1, 0), a3, voffA);
;             PG8_WAIT_V(8); PG8_WAIT_L(0); PG8_BAR; PG8_MMA(1, 0, At, B0); PG8_MMA(1, 1, At, B1); PG8_BAR; PG8_SCHED;
	s_add_i32 s26, s44, s28
	v_lshl_add_u64 v[146:147], v[146:147], 0, s[6:7]
	s_mov_b32 m0, s26
	ds_read_b128 v[188:191], v151 offset:49152
	ds_read_b128 v[192:195], v151 offset:50176
	ds_read_b128 v[196:199], v151 offset:51200
	ds_read_b128 v[200:203], v151 offset:52224
	ds_read_b128 v[204:207], v151 offset:53248
	ds_read_b128 v[208:211], v151 offset:54272
	ds_read_b128 v[212:215], v151 offset:55296
	ds_read_b128 v[216:219], v151 offset:56320
	global_load_lds_dwordx4 v[146:147], off
	s_add_i32 m0, s26, 0x2000
	s_add_u32 s24, s24, 0x80080
	v_lshl_add_u64 v[146:147], v[220:221], 0, s[6:7]
	s_addc_u32 s25, s25, 0
	s_add_i32 s26, s45, s28
	global_load_lds_dwordx4 v[146:147], off
	v_lshl_add_u64 v[146:147], s[24:25], 0, v[134:135]
	s_mov_b32 m0, s26
	s_nop 0
	global_load_lds_dwordx4 v[146:147], off
	v_lshl_add_u64 v[146:147], s[24:25], 0, v[130:131]
	s_add_i32 m0, s26, 0x2000
	s_nop 0
	global_load_lds_dwordx4 v[146:147], off
	v_lshl_add_u64 v[146:147], v[222:223], 0, s[6:7]
	s_mov_b32 m0, s36
	s_nop 0
	global_load_lds_dwordx4 v[146:147], off
	v_lshl_add_u64 v[146:147], v[224:225], 0, s[6:7]
	s_mov_b32 m0, s37
	s_nop 0
	global_load_lds_dwordx4 v[146:147], off
	s_waitcnt vmcnt(8)
	s_waitcnt lgkmcnt(0)
	s_barrier
	s_setprio 1
	v_mfma_f32_16x16x32_bf16 v[62:65], v[156:159], v[188:191], v[62:65]
	v_mfma_f32_16x16x32_bf16 v[58:61], v[164:167], v[188:191], v[58:61]
	v_mfma_f32_16x16x32_bf16 v[54:57], v[156:159], v[196:199], v[54:57]
	v_mfma_f32_16x16x32_bf16 v[46:49], v[164:167], v[196:199], v[46:49]
	v_mfma_f32_16x16x32_bf16 v[38:41], v[156:159], v[204:207], v[38:41]
	v_mfma_f32_16x16x32_bf16 v[30:33], v[164:167], v[204:207], v[30:33]
	v_mfma_f32_16x16x32_bf16 v[22:25], v[156:159], v[212:215], v[22:25]
	v_mfma_f32_16x16x32_bf16 v[14:17], v[164:167], v[212:215], v[14:17]
	v_mfma_f32_16x16x32_bf16 v[62:65], v[160:163], v[192:195], v[62:65]
	v_mfma_f32_16x16x32_bf16 v[58:61], v[168:171], v[192:195], v[58:61]
	v_mfma_f32_16x16x32_bf16 v[54:57], v[160:163], v[200:203], v[54:57]
	v_mfma_f32_16x16x32_bf16 v[46:49], v[168:171], v[200:203], v[46:49]
	v_mfma_f32_16x16x32_bf16 v[38:41], v[160:163], v[208:211], v[38:41]
	v_mfma_f32_16x16x32_bf16 v[30:33], v[168:171], v[208:211], v[30:33]
	v_mfma_f32_16x16x32_bf16 v[22:25], v[160:163], v[216:219], v[22:25]
	v_mfma_f32_16x16x32_bf16 v[14:17], v[168:171], v[216:219], v[14:17]
	s_setprio 0
	s_setprio 1
	v_mfma_f32_16x16x32_bf16 v[50:53], v[172:175], v[188:191], v[50:53]
	v_mfma_f32_16x16x32_bf16 v[42:45], v[180:183], v[188:191], v[42:45]
	v_mfma_f32_16x16x32_bf16 v[34:37], v[172:175], v[196:199], v[34:37]
	v_mfma_f32_16x16x32_bf16 v[26:29], v[180:183], v[196:199], v[26:29]
	v_mfma_f32_16x16x32_bf16 v[18:21], v[172:175], v[204:207], v[18:21]
	v_mfma_f32_16x16x32_bf16 v[10:13], v[180:183], v[204:207], v[10:13]
	v_mfma_f32_16x16x32_bf16 v[6:9], v[172:175], v[212:215], v[6:9]
	v_mfma_f32_16x16x32_bf16 v[2:5], v[180:183], v[212:215], v[2:5]
	v_mfma_f32_16x16x32_bf16 v[50:53], v[176:179], v[192:195], v[50:53]
	v_mfma_f32_16x16x32_bf16 v[42:45], v[184:187], v[192:195], v[42:45]
	v_mfma_f32_16x16x32_bf16 v[34:37], v[176:179], v[200:203], v[34:37]
	v_mfma_f32_16x16x32_bf16 v[26:29], v[184:187], v[200:203], v[26:29]
	v_mfma_f32_16x16x32_bf16 v[18:21], v[176:179], v[208:211], v[18:21]
	v_mfma_f32_16x16x32_bf16 v[10:13], v[184:187], v[208:211], v[10:13]
	v_mfma_f32_16x16x32_bf16 v[6:9], v[176:179], v[216:219], v[6:9]
	v_mfma_f32_16x16x32_bf16 v[2:5], v[184:187], v[216:219], v[2:5]
	s_setprio 0
	s_barrier
	s_add_i32 s58, s58, 2
	s_add_u32 s22, s22, 0x100
	s_addc_u32 s23, s23, 0
	s_add_u32 s51, s51, 0x100
	s_addc_u32 s55, s55, 0
	s_cmp_gt_u32 s58, 29
	s_cbranch_scc0 .LBB0_349
	s_and_b64 vcc, exec, s[10:11]
	s_cbranch_vccz .LBB0_352
	s_barrier

; #define PG8_STAGE(bufoff, gbase, voff) do { _Pragma("unroll") for (int _i = 0; _i < 2; ++_i) \
;         __builtin_amdgcn_global_load_lds((const unsigned*)((const char*)(gbase) + (voff)[_i]), (LAS unsigned*)(lds + (bufoff) + ldsw + _i * 8192), 16, 0, 0); } while (0)
; #define PG8_LDA(dst, b, h) do { _Pragma("unroll") for (int m = 0; m < 4; ++m) _Pragma("unroll") for (int k = 0; k < 2; ++k) dst[m][k] = *(const LAS bf16x8*)(lds + PG8_SA(b, h) + aoff + m * 2048 + k * 1024); } while (0)
; #define PG8_LDB(dst, b, h) do { _Pragma("unroll") for (int n = 0; n < 2; ++n) _Pragma("unroll") for (int k = 0; k < 2; ++k) dst[n][k] = *(const LAS bf16x8*)(lds + PG8_SB(b, h) + boff + n * 2048 + k * 1024); } while (0)
; #define PG8_MMA(ai, bj, At, Bt) do { __builtin_amdgcn_s_setprio(1); _Pragma("unroll") for (int m = 0; m < 4; ++m) _Pragma("unroll") for (int n = 0; n < 2; ++n) _Pragma("unroll") for (int k = 0; k < 2; ++k) \
;         acc[ai][bj][m][n] = __builtin_amdgcn_mfma_f32_16x16x32_bf16(Bt[n][k], At[m][k], acc[ai][bj][m][n], 0, 0, 0); __builtin_amdgcn_s_setprio(0); } while (0)
; #define PG8_WAIT_V(n) asm volatile("s_waitcnt vmcnt(" #n ")" ::: "memory")
; #define PG8_WAIT_L(n) asm volatile("s_waitcnt lgkmcnt(" #n ")" ::: "memory")
; #define PG8_BAR __builtin_amdgcn_s_barrier()
; #define PG8_SCHED __builtin_amdgcn_sched_barrier(0)
; template <class Epi, class Sched, bool ALIGN_EPI = false, bool SP2 = false>
; __device__ __forceinline__ void gemm_phase(LAS unsigned char* lds, const Gemm g, const Sched& S, const Epi& E) {
;     ...
;             const bool last = (t == nt - 2);
;             const char* a1 = cA + (size_t)(t + 1) * kstep;
;             const char* a2 = last ? nA : cA + (size_t)(t + 2) * kstep; const char* b2 = last ? nB : cB + (size_t)(t + 2) * kstep;
;             const char* a3 = a2 + kstep; const char* b3 = b2 + kstep;
;             if (last && has_next) S.a_ready(nxt);
;             if constexpr (SP2) {
;             PG8_LDB(B0, 0, 0); PG8_LDB(B1, 0, 1); PG8_SCHED; PG8_LDA(At, 0, 0); PG8_STAGE(PG8_SA(1, 1), a1 + hstepA, voffA);
;             PG8_WAIT_V(8); PG8_WAIT_L(0); PG8_BAR; PG8_MMA(0, 0, At, B0); PG8_MMA(0, 1, At, B1); PG8_BAR; PG8_SCHED;
;             PG8_LDA(At, 0, 1); PG8_STAGE(PG8_SB(0, 0), b2, voffB); PG8_STAGE(PG8_SB(0, 1), b2 + hstepB, voffB); PG8_STAGE(PG8_SA(0, 0), a2, voffA);
.LBB0_560:
	s_add_u32 s27, s20, s26
	s_addc_u32 s34, s21, 0
	s_add_u32 s30, s27, 0x100
	s_addc_u32 s31, s34, 0
	s_and_b64 s[28:29], s[24:25], exec
	s_cselect_b32 s29, s1, s31
	s_cselect_b32 s28, s0, s30
	s_add_u32 s26, s16, s26
	s_addc_u32 s30, s17, 0
	s_add_u32 s26, s26, 0x100
	s_addc_u32 s30, s30, 0
	s_and_b64 s[24:25], s[24:25], exec
	s_cselect_b32 s31, s19, s30
	s_cselect_b32 s30, s18, s26
	s_add_u32 s36, s27, 0x18080
	ds_read_b128 v[154:157], v147
	ds_read_b128 v[158:161], v147 offset:1024
	ds_read_b128 v[162:165], v147 offset:2048
	ds_read_b128 v[166:169], v147 offset:3072
	ds_read_b128 v[170:173], v148
	ds_read_b128 v[174:177], v148 offset:1024
	ds_read_b128 v[178:181], v148 offset:2048
	ds_read_b128 v[182:185], v148 offset:3072
	s_addc_u32 s37, s34, 0
	s_add_i32 s73, s54, s39
	s_add_i32 m0, s40, 0xc000
	s_add_i32 s76, s40, 0xe000
	s_add_i32 s70, s73, 0x2000
	s_add_u32 s34, s30, 0x18000
	s_addc_u32 s35, s31, 0
	s_add_i32 s72, s55, s39
	s_add_i32 s71, s72, 0x2000
	s_add_u32 s26, s28, 0x18000
	s_addc_u32 s27, s29, 0
	s_add_i32 s67, s57, s39
	s_add_i32 s65, s67, 0x2000
	s_add_u32 s24, s30, 0x18080
	s_addc_u32 s25, s31, 0
	s_add_i32 s66, s58, s39
	s_add_i32 s63, s66, 0x2000
	v_lshl_add_u64 v[218:219], s[36:37], 0, v[130:131]
	ds_read_b128 v[186:189], v149
	ds_read_b128 v[190:193], v149 offset:1024
	ds_read_b128 v[194:197], v149 offset:2048
	ds_read_b128 v[198:201], v149 offset:3072
	ds_read_b128 v[202:205], v149 offset:4096
	ds_read_b128 v[206:209], v149 offset:5120
	ds_read_b128 v[210:213], v149 offset:6144
	ds_read_b128 v[214:217], v149 offset:7168
	global_load_lds_dwordx4 v[218:219], off
	v_lshl_add_u64 v[218:219], s[36:37], 0, v[134:135]
	s_mov_b32 m0, s76
	s_nop 0
	global_load_lds_dwordx4 v[218:219], off
	s_waitcnt vmcnt(8)
	s_waitcnt lgkmcnt(0)
	s_barrier
	s_setprio 1
	v_mfma_f32_16x16x32_bf16 v[126:129], v[154:157], v[186:189], v[126:129]
	v_mfma_f32_16x16x32_bf16 v[122:125], v[162:165], v[186:189], v[122:125]
	v_mfma_f32_16x16x32_bf16 v[118:121], v[154:157], v[194:197], v[118:121]
	v_mfma_f32_16x16x32_bf16 v[110:113], v[162:165], v[194:197], v[110:113]
	v_mfma_f32_16x16x32_bf16 v[102:105], v[154:157], v[202:205], v[102:105]
	v_mfma_f32_16x16x32_bf16 v[94:97], v[162:165], v[202:205], v[94:97]
	v_mfma_f32_16x16x32_bf16 v[86:89], v[154:157], v[210:213], v[86:89]
	v_mfma_f32_16x16x32_bf16 v[78:81], v[162:165], v[210:213], v[78:81]
	v_mfma_f32_16x16x32_bf16 v[126:129], v[158:161], v[190:193], v[126:129]
	v_mfma_f32_16x16x32_bf16 v[122:125], v[166:169], v[190:193], v[122:125]
	v_mfma_f32_16x16x32_bf16 v[118:121], v[158:161], v[198:201], v[118:121]
	v_mfma_f32_16x16x32_bf16 v[110:113], v[166:169], v[198:201], v[110:113]
	v_mfma_f32_16x16x32_bf16 v[102:105], v[158:161], v[206:209], v[102:105]
	v_mfma_f32_16x16x32_bf16 v[94:97], v[166:169], v[206:209], v[94:97]
	v_mfma_f32_16x16x32_bf16 v[86:89], v[158:161], v[214:217], v[86:89]
	v_mfma_f32_16x16x32_bf16 v[78:81], v[166:169], v[214:217], v[78:81]
	s_setprio 0
	s_setprio 1
	v_mfma_f32_16x16x32_bf16 v[114:117], v[170:173], v[186:189], v[114:117]
	v_mfma_f32_16x16x32_bf16 v[106:109], v[178:181], v[186:189], v[106:109]
	v_mfma_f32_16x16x32_bf16 v[98:101], v[170:173], v[194:197], v[98:101]
	v_mfma_f32_16x16x32_bf16 v[90:93], v[178:181], v[194:197], v[90:93]
	v_mfma_f32_16x16x32_bf16 v[82:85], v[170:173], v[202:205], v[82:85]
	v_mfma_f32_16x16x32_bf16 v[74:77], v[178:181], v[202:205], v[74:77]
	v_mfma_f32_16x16x32_bf16 v[70:73], v[170:173], v[210:213], v[70:73]
	v_mfma_f32_16x16x32_bf16 v[66:69], v[178:181], v[210:213], v[66:69]
	v_mfma_f32_16x16x32_bf16 v[114:117], v[174:177], v[190:193], v[114:117]
	v_mfma_f32_16x16x32_bf16 v[106:109], v[182:185], v[190:193], v[106:109]
	v_mfma_f32_16x16x32_bf16 v[98:101], v[174:177], v[198:201], v[98:101]
	v_mfma_f32_16x16x32_bf16 v[90:93], v[182:185], v[198:201], v[90:93]
	v_mfma_f32_16x16x32_bf16 v[82:85], v[174:177], v[206:209], v[82:85]
	v_mfma_f32_16x16x32_bf16 v[74:77], v[182:185], v[206:209], v[74:77]
	v_mfma_f32_16x16x32_bf16 v[70:73], v[174:177], v[214:217], v[70:73]
	v_mfma_f32_16x16x32_bf16 v[66:69], v[182:185], v[214:217], v[66:69]
	s_setprio 0
	s_barrier
	s_mov_b32 m0, s73
	v_lshl_add_u64 v[218:219], s[30:31], 0, v[132:133]
	ds_read_b128 v[186:189], v149 offset:16384
	ds_read_b128 v[190:193], v149 offset:17408
	ds_read_b128 v[194:197], v149 offset:18432
	ds_read_b128 v[198:201], v149 offset:19456
	ds_read_b128 v[202:205], v149 offset:20480
	ds_read_b128 v[206:209], v149 offset:21504
	ds_read_b128 v[210:213], v149 offset:22528
	ds_read_b128 v[214:217], v149 offset:23552
	global_load_lds_dwordx4 v[218:219], off
	v_lshl_add_u64 v[220:221], s[30:31], 0, v[136:137]
	s_mov_b32 m0, s70
	v_lshl_add_u64 v[222:223], s[34:35], 0, v[132:133]
	global_load_lds_dwordx4 v[220:221], off
	s_mov_b32 m0, s72
	v_lshl_add_u64 v[224:225], s[28:29], 0, v[134:135]
	global_load_lds_dwordx4 v[222:223], off
	v_lshl_add_u64 v[222:223], s[34:35], 0, v[136:137]
	s_mov_b32 m0, s71
	s_nop 0
	global_load_lds_dwordx4 v[222:223], off
	v_lshl_add_u64 v[222:223], s[28:29], 0, v[130:131]
	s_mov_b32 m0, s40
	s_nop 0
	global_load_lds_dwordx4 v[222:223], off
	s_mov_b32 m0, s33
	s_nop 0
	global_load_lds_dwordx4 v[224:225], off
	s_waitcnt vmcnt(8)
	s_waitcnt lgkmcnt(0)
	s_barrier
; #define PG8_STAGE(bufoff, gbase, voff) do { _Pragma("unroll") for (int _i = 0; _i < 2; ++_i) \
;         __builtin_amdgcn_global_load_lds((const unsigned*)((const char*)(gbase) + (voff)[_i]), (LAS unsigned*)(lds + (bufoff) + ldsw + _i * 8192), 16, 0, 0); } while (0)
; #define PG8_LDA(dst, b, h) do { _Pragma("unroll") for (int m = 0; m < 4; ++m) _Pragma("unroll") for (int k = 0; k < 2; ++k) dst[m][k] = *(const LAS bf16x8*)(lds + PG8_SA(b, h) + aoff + m * 2048 + k * 1024); } while (0)
; #define PG8_LDB(dst, b, h) do { _Pragma("unroll") for (int n = 0; n < 2; ++n) _Pragma("unroll") for (int k = 0; k < 2; ++k) dst[n][k] = *(const LAS bf16x8*)(lds + PG8_SB(b, h) + boff + n * 2048 + k * 1024); } while (0)
; #define PG8_MMA(ai, bj, At, Bt) do { __builtin_amdgcn_s_setprio(1); _Pragma("unroll") for (int m = 0; m < 4; ++m) _Pragma("unroll") for (int n = 0; n < 2; ++n) _Pragma("unroll") for (int k = 0; k < 2; ++k) \
;         acc[ai][bj][m][n] = __builtin_amdgcn_mfma_f32_16x16x32_bf16(Bt[n][k], At[m][k], acc[ai][bj][m][n], 0, 0, 0); __builtin_amdgcn_s_setprio(0); } while (0)
; #define PG8_WAIT_V(n) asm volatile("s_waitcnt vmcnt(" #n ")" ::: "memory")
; #define PG8_WAIT_L(n) asm volatile("s_waitcnt lgkmcnt(" #n ")" ::: "memory")
; #define PG8_BAR __builtin_amdgcn_s_barrier()
; #define PG8_SCHED __builtin_amdgcn_sched_barrier(0)
; template <class Epi, class Sched, bool ALIGN_EPI = false, bool SP2 = false>
; __device__ __forceinline__ void gemm_phase(LAS unsigned char* lds, const Gemm g, const Sched& S, const Epi& E) {
;     ...
;             PG8_WAIT_V(8); PG8_WAIT_L(0); PG8_BAR; PG8_MMA(1, 0, At, B0); PG8_MMA(1, 1, At, B1); PG8_BAR; PG8_SCHED;
;             PG8_LDB(B0, 1, 0); PG8_LDB(B1, 1, 1); PG8_SCHED; PG8_LDA(At, 1, 0); PG8_STAGE(PG8_SA(0, 1), a2 + hstepA, voffA);
;             PG8_WAIT_V(8); PG8_WAIT_L(0); PG8_BAR; PG8_MMA(0, 0, At, B0); PG8_MMA(0, 1, At, B1); PG8_BAR; PG8_SCHED;
	s_setprio 1
	v_mfma_f32_16x16x32_bf16 v[62:65], v[154:157], v[186:189], v[62:65]
	v_mfma_f32_16x16x32_bf16 v[58:61], v[162:165], v[186:189], v[58:61]
	v_mfma_f32_16x16x32_bf16 v[54:57], v[154:157], v[194:197], v[54:57]
	v_mfma_f32_16x16x32_bf16 v[46:49], v[162:165], v[194:197], v[46:49]
	v_mfma_f32_16x16x32_bf16 v[38:41], v[154:157], v[202:205], v[38:41]
	v_mfma_f32_16x16x32_bf16 v[30:33], v[162:165], v[202:205], v[30:33]
	v_mfma_f32_16x16x32_bf16 v[22:25], v[154:157], v[210:213], v[22:25]
	v_mfma_f32_16x16x32_bf16 v[14:17], v[162:165], v[210:213], v[14:17]
	v_mfma_f32_16x16x32_bf16 v[62:65], v[158:161], v[190:193], v[62:65]
	v_mfma_f32_16x16x32_bf16 v[58:61], v[166:169], v[190:193], v[58:61]
	v_mfma_f32_16x16x32_bf16 v[54:57], v[158:161], v[198:201], v[54:57]
	v_mfma_f32_16x16x32_bf16 v[46:49], v[166:169], v[198:201], v[46:49]
	v_mfma_f32_16x16x32_bf16 v[38:41], v[158:161], v[206:209], v[38:41]
	v_mfma_f32_16x16x32_bf16 v[30:33], v[166:169], v[206:209], v[30:33]
	v_mfma_f32_16x16x32_bf16 v[22:25], v[158:161], v[214:217], v[22:25]
	v_mfma_f32_16x16x32_bf16 v[14:17], v[166:169], v[214:217], v[14:17]
	s_setprio 0
	s_setprio 1
	v_mfma_f32_16x16x32_bf16 v[50:53], v[170:173], v[186:189], v[50:53]
	v_mfma_f32_16x16x32_bf16 v[42:45], v[178:181], v[186:189], v[42:45]
	v_mfma_f32_16x16x32_bf16 v[34:37], v[170:173], v[194:197], v[34:37]
	v_mfma_f32_16x16x32_bf16 v[26:29], v[178:181], v[194:197], v[26:29]
	v_mfma_f32_16x16x32_bf16 v[18:21], v[170:173], v[202:205], v[18:21]
	v_mfma_f32_16x16x32_bf16 v[10:13], v[178:181], v[202:205], v[10:13]
	v_mfma_f32_16x16x32_bf16 v[6:9], v[170:173], v[210:213], v[6:9]
	v_mfma_f32_16x16x32_bf16 v[2:5], v[178:181], v[210:213], v[2:5]
	v_mfma_f32_16x16x32_bf16 v[50:53], v[174:177], v[190:193], v[50:53]
	v_mfma_f32_16x16x32_bf16 v[42:45], v[182:185], v[190:193], v[42:45]
	v_mfma_f32_16x16x32_bf16 v[34:37], v[174:177], v[198:201], v[34:37]
	v_mfma_f32_16x16x32_bf16 v[26:29], v[182:185], v[198:201], v[26:29]
	v_mfma_f32_16x16x32_bf16 v[18:21], v[174:177], v[206:209], v[18:21]
	v_mfma_f32_16x16x32_bf16 v[10:13], v[182:185], v[206:209], v[10:13]
	v_mfma_f32_16x16x32_bf16 v[6:9], v[174:177], v[214:217], v[6:9]
	v_mfma_f32_16x16x32_bf16 v[2:5], v[182:185], v[214:217], v[2:5]
	s_setprio 0
	s_barrier
	ds_read_b128 v[154:157], v150
	ds_read_b128 v[158:161], v150 offset:1024
	ds_read_b128 v[162:165], v150 offset:2048
	ds_read_b128 v[166:169], v150 offset:3072
	ds_read_b128 v[170:173], v151
	ds_read_b128 v[174:177], v151 offset:1024
	ds_read_b128 v[178:181], v151 offset:2048
	ds_read_b128 v[182:185], v151 offset:3072
	s_mov_b32 m0, s41
	v_lshl_add_u64 v[226:227], s[26:27], 0, v[130:131]
	ds_read_b128 v[186:189], v149 offset:32768
	ds_read_b128 v[190:193], v149 offset:33792
	ds_read_b128 v[194:197], v149 offset:34816
	ds_read_b128 v[198:201], v149 offset:35840
	ds_read_b128 v[202:205], v149 offset:36864
	ds_read_b128 v[206:209], v149 offset:37888
	ds_read_b128 v[210:213], v149 offset:38912
	ds_read_b128 v[214:217], v149 offset:39936
	global_load_lds_dwordx4 v[226:227], off
	v_lshl_add_u64 v[226:227], s[26:27], 0, v[134:135]
	s_mov_b32 m0, s44
	s_nop 0
	global_load_lds_dwordx4 v[226:227], off
	s_waitcnt vmcnt(8)
	s_waitcnt lgkmcnt(0)
	s_barrier
	s_setprio 1
	v_mfma_f32_16x16x32_bf16 v[126:129], v[154:157], v[186:189], v[126:129]
	v_mfma_f32_16x16x32_bf16 v[122:125], v[162:165], v[186:189], v[122:125]
	v_mfma_f32_16x16x32_bf16 v[118:121], v[154:157], v[194:197], v[118:121]
	v_mfma_f32_16x16x32_bf16 v[110:113], v[162:165], v[194:197], v[110:113]
	v_mfma_f32_16x16x32_bf16 v[102:105], v[154:157], v[202:205], v[102:105]
	v_mfma_f32_16x16x32_bf16 v[94:97], v[162:165], v[202:205], v[94:97]
	v_mfma_f32_16x16x32_bf16 v[86:89], v[154:157], v[210:213], v[86:89]
	v_mfma_f32_16x16x32_bf16 v[78:81], v[162:165], v[210:213], v[78:81]
	v_mfma_f32_16x16x32_bf16 v[126:129], v[158:161], v[190:193], v[126:129]
	v_mfma_f32_16x16x32_bf16 v[122:125], v[166:169], v[190:193], v[122:125]
	v_mfma_f32_16x16x32_bf16 v[118:121], v[158:161], v[198:201], v[118:121]
	v_mfma_f32_16x16x32_bf16 v[110:113], v[166:169], v[198:201], v[110:113]
	v_mfma_f32_16x16x32_bf16 v[102:105], v[158:161], v[206:209], v[102:105]
	v_mfma_f32_16x16x32_bf16 v[94:97], v[166:169], v[206:209], v[94:97]
	v_mfma_f32_16x16x32_bf16 v[86:89], v[158:161], v[214:217], v[86:89]
	v_mfma_f32_16x16x32_bf16 v[78:81], v[166:169], v[214:217], v[78:81]
	s_setprio 0
	s_setprio 1
	v_mfma_f32_16x16x32_bf16 v[114:117], v[170:173], v[186:189], v[114:117]
	v_mfma_f32_16x16x32_bf16 v[106:109], v[178:181], v[186:189], v[106:109]
	v_mfma_f32_16x16x32_bf16 v[98:101], v[170:173], v[194:197], v[98:101]
	v_mfma_f32_16x16x32_bf16 v[90:93], v[178:181], v[194:197], v[90:93]
	v_mfma_f32_16x16x32_bf16 v[82:85], v[170:173], v[202:205], v[82:85]
	v_mfma_f32_16x16x32_bf16 v[74:77], v[178:181], v[202:205], v[74:77]
	v_mfma_f32_16x16x32_bf16 v[70:73], v[170:173], v[210:213], v[70:73]
	v_mfma_f32_16x16x32_bf16 v[66:69], v[178:181], v[210:213], v[66:69]
	v_mfma_f32_16x16x32_bf16 v[114:117], v[174:177], v[190:193], v[114:117]
	v_mfma_f32_16x16x32_bf16 v[106:109], v[182:185], v[190:193], v[106:109]
	v_mfma_f32_16x16x32_bf16 v[98:101], v[174:177], v[198:201], v[98:101]
	v_mfma_f32_16x16x32_bf16 v[90:93], v[182:185], v[198:201], v[90:93]
	v_mfma_f32_16x16x32_bf16 v[82:85], v[174:177], v[206:209], v[82:85]
	v_mfma_f32_16x16x32_bf16 v[74:77], v[182:185], v[206:209], v[74:77]
	v_mfma_f32_16x16x32_bf16 v[70:73], v[174:177], v[214:217], v[70:73]
	v_mfma_f32_16x16x32_bf16 v[66:69], v[182:185], v[214:217], v[66:69]
	s_setprio 0
	s_barrier
; #define PG8_STAGE(bufoff, gbase, voff) do { _Pragma("unroll") for (int _i = 0; _i < 2; ++_i) \
;         __builtin_amdgcn_global_load_lds((const unsigned*)((const char*)(gbase) + (voff)[_i]), (LAS unsigned*)(lds + (bufoff) + ldsw + _i * 8192), 16, 0, 0); } while (0)
; #define PG8_LDA(dst, b, h) do { _Pragma("unroll") for (int m = 0; m < 4; ++m) _Pragma("unroll") for (int k = 0; k < 2; ++k) dst[m][k] = *(const LAS bf16x8*)(lds + PG8_SA(b, h) + aoff + m * 2048 + k * 1024); } while (0)
; #define PG8_MMA(ai, bj, At, Bt) do { __builtin_amdgcn_s_setprio(1); _Pragma("unroll") for (int m = 0; m < 4; ++m) _Pragma("unroll") for (int n = 0; n < 2; ++n) _Pragma("unroll") for (int k = 0; k < 2; ++k) \
;         acc[ai][bj][m][n] = __builtin_amdgcn_mfma_f32_16x16x32_bf16(Bt[n][k], At[m][k], acc[ai][bj][m][n], 0, 0, 0); __builtin_amdgcn_s_setprio(0); } while (0)
; #define PG8_WAIT_V(n) asm volatile("s_waitcnt vmcnt(" #n ")" ::: "memory")
; #define PG8_WAIT_L(n) asm volatile("s_waitcnt lgkmcnt(" #n ")" ::: "memory")
; #define PG8_BAR __builtin_amdgcn_s_barrier()
; #define PG8_SCHED __builtin_amdgcn_sched_barrier(0)
; template <class Epi, class Sched, bool ALIGN_EPI = false, bool SP2 = false>
; __device__ __forceinline__ void gemm_phase(LAS unsigned char* lds, const Gemm g, const Sched& S, const Epi& E) {
;     ...
;             PG8_LDA(At, 1, 1); PG8_STAGE(PG8_SB(1, 0), b3, voffB); PG8_STAGE(PG8_SB(1, 1), b3 + hstepB, voffB); PG8_STAGE(PG8_SA(1, 0), a3, voffA);
;             PG8_WAIT_V(8); PG8_WAIT_L(0); PG8_BAR; PG8_MMA(1, 0, At, B0); PG8_MMA(1, 1, At, B1); PG8_BAR; PG8_SCHED;
	s_mov_b32 m0, s67
	v_lshl_add_u64 v[218:219], v[218:219], 0, s[12:13]
	ds_read_b128 v[186:189], v149 offset:49152
	ds_read_b128 v[190:193], v149 offset:50176
	ds_read_b128 v[194:197], v149 offset:51200
	ds_read_b128 v[198:201], v149 offset:52224
	ds_read_b128 v[202:205], v149 offset:53248
	ds_read_b128 v[206:209], v149 offset:54272
	ds_read_b128 v[210:213], v149 offset:55296
	ds_read_b128 v[214:217], v149 offset:56320
	global_load_lds_dwordx4 v[218:219], off
	v_lshl_add_u64 v[218:219], v[220:221], 0, s[12:13]
	s_mov_b32 m0, s65
	s_nop 0
	global_load_lds_dwordx4 v[218:219], off
	v_lshl_add_u64 v[218:219], s[24:25], 0, v[132:133]
	s_mov_b32 m0, s66
	s_nop 0
	global_load_lds_dwordx4 v[218:219], off
	v_lshl_add_u64 v[218:219], s[24:25], 0, v[136:137]
	s_mov_b32 m0, s63
	s_nop 0
	global_load_lds_dwordx4 v[218:219], off
	v_lshl_add_u64 v[218:219], v[222:223], 0, s[12:13]
	s_mov_b32 m0, s45
	s_nop 0
	global_load_lds_dwordx4 v[218:219], off
	v_lshl_add_u64 v[218:219], v[224:225], 0, s[12:13]
	s_mov_b32 m0, s46
	s_nop 0
	global_load_lds_dwordx4 v[218:219], off
	s_waitcnt vmcnt(8)
	s_waitcnt lgkmcnt(0)
	s_barrier
	s_setprio 1
	v_mfma_f32_16x16x32_bf16 v[62:65], v[154:157], v[186:189], v[62:65]
	v_mfma_f32_16x16x32_bf16 v[58:61], v[162:165], v[186:189], v[58:61]
	v_mfma_f32_16x16x32_bf16 v[54:57], v[154:157], v[194:197], v[54:57]
	v_mfma_f32_16x16x32_bf16 v[46:49], v[162:165], v[194:197], v[46:49]
	v_mfma_f32_16x16x32_bf16 v[38:41], v[154:157], v[202:205], v[38:41]
	v_mfma_f32_16x16x32_bf16 v[30:33], v[162:165], v[202:205], v[30:33]
	v_mfma_f32_16x16x32_bf16 v[22:25], v[154:157], v[210:213], v[22:25]
	v_mfma_f32_16x16x32_bf16 v[14:17], v[162:165], v[210:213], v[14:17]
	v_mfma_f32_16x16x32_bf16 v[62:65], v[158:161], v[190:193], v[62:65]
	v_mfma_f32_16x16x32_bf16 v[58:61], v[166:169], v[190:193], v[58:61]
	v_mfma_f32_16x16x32_bf16 v[54:57], v[158:161], v[198:201], v[54:57]
	v_mfma_f32_16x16x32_bf16 v[46:49], v[166:169], v[198:201], v[46:49]
	v_mfma_f32_16x16x32_bf16 v[38:41], v[158:161], v[206:209], v[38:41]
	v_mfma_f32_16x16x32_bf16 v[30:33], v[166:169], v[206:209], v[30:33]
	v_mfma_f32_16x16x32_bf16 v[22:25], v[158:161], v[214:217], v[22:25]
	v_mfma_f32_16x16x32_bf16 v[14:17], v[166:169], v[214:217], v[14:17]
	s_setprio 0
	s_setprio 1
	v_mfma_f32_16x16x32_bf16 v[50:53], v[170:173], v[186:189], v[50:53]
	v_mfma_f32_16x16x32_bf16 v[42:45], v[178:181], v[186:189], v[42:45]
	v_mfma_f32_16x16x32_bf16 v[34:37], v[170:173], v[194:197], v[34:37]
	v_mfma_f32_16x16x32_bf16 v[26:29], v[178:181], v[194:197], v[26:29]
	v_mfma_f32_16x16x32_bf16 v[18:21], v[170:173], v[202:205], v[18:21]
	v_mfma_f32_16x16x32_bf16 v[10:13], v[178:181], v[202:205], v[10:13]
	v_mfma_f32_16x16x32_bf16 v[6:9], v[170:173], v[210:213], v[6:9]
	v_mfma_f32_16x16x32_bf16 v[2:5], v[178:181], v[210:213], v[2:5]
	v_mfma_f32_16x16x32_bf16 v[50:53], v[174:177], v[190:193], v[50:53]
	v_mfma_f32_16x16x32_bf16 v[42:45], v[182:185], v[190:193], v[42:45]
	v_mfma_f32_16x16x32_bf16 v[34:37], v[174:177], v[198:201], v[34:37]
	v_mfma_f32_16x16x32_bf16 v[26:29], v[182:185], v[198:201], v[26:29]
	v_mfma_f32_16x16x32_bf16 v[18:21], v[174:177], v[206:209], v[18:21]
	v_mfma_f32_16x16x32_bf16 v[10:13], v[182:185], v[206:209], v[10:13]
	v_mfma_f32_16x16x32_bf16 v[6:9], v[174:177], v[214:217], v[6:9]
	v_mfma_f32_16x16x32_bf16 v[2:5], v[182:185], v[214:217], v[2:5]
	s_setprio 0
	s_barrier
	s_movk_i32 s26, 0x100
	s_andn2_b64 vcc, exec, s[22:23]
	s_mov_b64 s[24:25], -1
	s_mov_b64 s[22:23], 0
	s_cbranch_vccz .LBB0_560
	s_and_b64 vcc, exec, s[14:15]
	s_cbranch_vccz .LBB0_563
	s_barrier

; #define PG8_STAGE(bufoff, gbase, voff) do { _Pragma("unroll") for (int _i = 0; _i < 2; ++_i) \
;         __builtin_amdgcn_global_load_lds((const unsigned*)((const char*)(gbase) + (voff)[_i]), (LAS unsigned*)(lds + (bufoff) + ldsw + _i * 8192), 16, 0, 0); } while (0)
; #define PG8_LDA(dst, b, h) do { _Pragma("unroll") for (int m = 0; m < 4; ++m) _Pragma("unroll") for (int k = 0; k < 2; ++k) dst[m][k] = *(const LAS bf16x8*)(lds + PG8_SA(b, h) + aoff + m * 2048 + k * 1024); } while (0)
; #define PG8_LDB(dst, b, h) do { _Pragma("unroll") for (int n = 0; n < 2; ++n) _Pragma("unroll") for (int k = 0; k < 2; ++k) dst[n][k] = *(const LAS bf16x8*)(lds + PG8_SB(b, h) + boff + n * 2048 + k * 1024); } while (0)
; #define PG8_MMA(ai, bj, At, Bt) do { __builtin_amdgcn_s_setprio(1); _Pragma("unroll") for (int m = 0; m < 4; ++m) _Pragma("unroll") for (int n = 0; n < 2; ++n) _Pragma("unroll") for (int k = 0; k < 2; ++k) \
;         acc[ai][bj][m][n] = __builtin_amdgcn_mfma_f32_16x16x32_bf16(Bt[n][k], At[m][k], acc[ai][bj][m][n], 0, 0, 0); __builtin_amdgcn_s_setprio(0); } while (0)
; #define PG8_WAIT_V(n) asm volatile("s_waitcnt vmcnt(" #n ")" ::: "memory")
; #define PG8_WAIT_L(n) asm volatile("s_waitcnt lgkmcnt(" #n ")" ::: "memory")
; #define PG8_BAR __builtin_amdgcn_s_barrier()
; #define PG8_SCHED __builtin_amdgcn_sched_barrier(0)
; template <class Epi, class Sched, bool ALIGN_EPI = false, bool SP2 = false>
; __device__ __forceinline__ void gemm_phase(LAS unsigned char* lds, const Gemm g, const Sched& S, const Epi& E) {
;     ...
;             const bool last = (t == nt - 2);
;             const char* a1 = cA + (size_t)(t + 1) * kstep;
;             const char* a2 = last ? nA : cA + (size_t)(t + 2) * kstep; const char* b2 = last ? nB : cB + (size_t)(t + 2) * kstep;
;             const char* a3 = a2 + kstep; const char* b3 = b2 + kstep;
;             if (last && has_next) S.a_ready(nxt);
;             if constexpr (SP2) {
;             PG8_LDB(B0, 0, 0); PG8_LDB(B1, 0, 1); PG8_SCHED; PG8_LDA(At, 0, 0); PG8_STAGE(PG8_SA(1, 1), a1 + hstepA, voffA);
;             PG8_WAIT_V(8); PG8_WAIT_L(0); PG8_BAR; PG8_MMA(0, 0, At, B0); PG8_MMA(0, 1, At, B1); PG8_BAR; PG8_SCHED;
;             PG8_LDA(At, 0, 1); PG8_STAGE(PG8_SB(0, 0), b2, voffB); PG8_STAGE(PG8_SB(0, 1), b2 + hstepB, voffB); PG8_STAGE(PG8_SA(0, 0), a2, voffA);
.LBB0_588:
	s_add_u32 s27, s20, s26
	s_addc_u32 s34, s21, 0
	s_add_u32 s30, s27, 0x100
	s_addc_u32 s31, s34, 0
	s_and_b64 s[28:29], s[24:25], exec
	s_cselect_b32 s29, s1, s31
	s_cselect_b32 s28, s0, s30
	s_add_u32 s26, s18, s26
	s_addc_u32 s30, s19, 0
	s_add_u32 s26, s26, 0x100
	s_addc_u32 s30, s30, 0
	s_and_b64 s[24:25], s[24:25], exec
	s_cselect_b32 s31, s17, s30
	s_cselect_b32 s30, s16, s26
	s_add_u32 s36, s27, 0x18080
	ds_read_b128 v[148:151], v142
	ds_read_b128 v[154:157], v142 offset:1024
	ds_read_b128 v[158:161], v142 offset:2048
	ds_read_b128 v[162:165], v142 offset:3072
	ds_read_b128 v[166:169], v143
	ds_read_b128 v[170:173], v143 offset:1024
	ds_read_b128 v[174:177], v143 offset:2048
	ds_read_b128 v[178:181], v143 offset:3072
	s_addc_u32 s37, s34, 0
	s_add_i32 s77, s56, s44
	s_add_i32 m0, s45, 0xc000
	s_add_i32 s78, s45, 0xe000
	s_add_i32 s72, s77, 0x2000
	s_add_u32 s34, s30, 0x18000
	s_addc_u32 s35, s31, 0
	s_add_i32 s76, s57, s44
	s_add_i32 s73, s76, 0x2000
	s_add_u32 s26, s28, 0x18000
	s_addc_u32 s27, s29, 0
	s_add_i32 s71, s59, s44
	s_add_i32 s67, s71, 0x2000
	s_add_u32 s24, s30, 0x18080
	s_addc_u32 s25, s31, 0
	s_add_i32 s70, s60, s44
	s_add_i32 s66, s70, 0x2000
	v_lshl_add_u64 v[214:215], s[36:37], 0, v[130:131]
	ds_read_b128 v[182:185], v144
	ds_read_b128 v[186:189], v144 offset:1024
	ds_read_b128 v[190:193], v144 offset:2048
	ds_read_b128 v[194:197], v144 offset:3072
	ds_read_b128 v[198:201], v144 offset:4096
	ds_read_b128 v[202:205], v144 offset:5120
	ds_read_b128 v[206:209], v144 offset:6144
	ds_read_b128 v[210:213], v144 offset:7168
	global_load_lds_dwordx4 v[214:215], off
	v_lshl_add_u64 v[214:215], s[36:37], 0, v[134:135]
	s_mov_b32 m0, s78
	s_nop 0
	global_load_lds_dwordx4 v[214:215], off
	s_waitcnt vmcnt(8)
	s_waitcnt lgkmcnt(0)
	s_barrier
	s_setprio 1
	v_mfma_f32_16x16x32_bf16 v[126:129], v[148:151], v[182:185], v[126:129]
	v_mfma_f32_16x16x32_bf16 v[122:125], v[158:161], v[182:185], v[122:125]
	v_mfma_f32_16x16x32_bf16 v[118:121], v[148:151], v[190:193], v[118:121]
	v_mfma_f32_16x16x32_bf16 v[110:113], v[158:161], v[190:193], v[110:113]
	v_mfma_f32_16x16x32_bf16 v[102:105], v[148:151], v[198:201], v[102:105]
	v_mfma_f32_16x16x32_bf16 v[94:97], v[158:161], v[198:201], v[94:97]
	v_mfma_f32_16x16x32_bf16 v[86:89], v[148:151], v[206:209], v[86:89]
	v_mfma_f32_16x16x32_bf16 v[78:81], v[158:161], v[206:209], v[78:81]
	v_mfma_f32_16x16x32_bf16 v[126:129], v[154:157], v[186:189], v[126:129]
	v_mfma_f32_16x16x32_bf16 v[122:125], v[162:165], v[186:189], v[122:125]
	v_mfma_f32_16x16x32_bf16 v[118:121], v[154:157], v[194:197], v[118:121]
	v_mfma_f32_16x16x32_bf16 v[110:113], v[162:165], v[194:197], v[110:113]
	v_mfma_f32_16x16x32_bf16 v[102:105], v[154:157], v[202:205], v[102:105]
	v_mfma_f32_16x16x32_bf16 v[94:97], v[162:165], v[202:205], v[94:97]
	v_mfma_f32_16x16x32_bf16 v[86:89], v[154:157], v[210:213], v[86:89]
	v_mfma_f32_16x16x32_bf16 v[78:81], v[162:165], v[210:213], v[78:81]
	s_setprio 0
	s_setprio 1
	v_mfma_f32_16x16x32_bf16 v[114:117], v[166:169], v[182:185], v[114:117]
	v_mfma_f32_16x16x32_bf16 v[106:109], v[174:177], v[182:185], v[106:109]
	v_mfma_f32_16x16x32_bf16 v[98:101], v[166:169], v[190:193], v[98:101]
	v_mfma_f32_16x16x32_bf16 v[90:93], v[174:177], v[190:193], v[90:93]
	v_mfma_f32_16x16x32_bf16 v[82:85], v[166:169], v[198:201], v[82:85]
	v_mfma_f32_16x16x32_bf16 v[74:77], v[174:177], v[198:201], v[74:77]
	v_mfma_f32_16x16x32_bf16 v[70:73], v[166:169], v[206:209], v[70:73]
	v_mfma_f32_16x16x32_bf16 v[66:69], v[174:177], v[206:209], v[66:69]
	v_mfma_f32_16x16x32_bf16 v[114:117], v[170:173], v[186:189], v[114:117]
	v_mfma_f32_16x16x32_bf16 v[106:109], v[178:181], v[186:189], v[106:109]
	v_mfma_f32_16x16x32_bf16 v[98:101], v[170:173], v[194:197], v[98:101]
	v_mfma_f32_16x16x32_bf16 v[90:93], v[178:181], v[194:197], v[90:93]
	v_mfma_f32_16x16x32_bf16 v[82:85], v[170:173], v[202:205], v[82:85]
	v_mfma_f32_16x16x32_bf16 v[74:77], v[178:181], v[202:205], v[74:77]
	v_mfma_f32_16x16x32_bf16 v[70:73], v[170:173], v[210:213], v[70:73]
	v_mfma_f32_16x16x32_bf16 v[66:69], v[178:181], v[210:213], v[66:69]
	s_setprio 0
	s_barrier
	s_mov_b32 m0, s77
	v_lshl_add_u64 v[214:215], s[30:31], 0, v[132:133]
	ds_read_b128 v[182:185], v144 offset:16384
	ds_read_b128 v[186:189], v144 offset:17408
	ds_read_b128 v[190:193], v144 offset:18432
	ds_read_b128 v[194:197], v144 offset:19456
	ds_read_b128 v[198:201], v144 offset:20480
	ds_read_b128 v[202:205], v144 offset:21504
	ds_read_b128 v[206:209], v144 offset:22528
	ds_read_b128 v[210:213], v144 offset:23552
	global_load_lds_dwordx4 v[214:215], off
	v_lshl_add_u64 v[216:217], s[30:31], 0, v[136:137]
	s_mov_b32 m0, s72
	v_lshl_add_u64 v[218:219], s[34:35], 0, v[132:133]
	global_load_lds_dwordx4 v[216:217], off
	s_mov_b32 m0, s76
	v_lshl_add_u64 v[220:221], s[28:29], 0, v[134:135]
	global_load_lds_dwordx4 v[218:219], off
	v_lshl_add_u64 v[218:219], s[34:35], 0, v[136:137]
	s_mov_b32 m0, s73
	s_nop 0
	global_load_lds_dwordx4 v[218:219], off
	v_lshl_add_u64 v[218:219], s[28:29], 0, v[130:131]
	s_mov_b32 m0, s45
	s_nop 0
	global_load_lds_dwordx4 v[218:219], off
	s_mov_b32 m0, s46
	s_nop 0
	global_load_lds_dwordx4 v[220:221], off
	s_waitcnt vmcnt(8)
	s_waitcnt lgkmcnt(0)
	s_barrier
; #define PG8_STAGE(bufoff, gbase, voff) do { _Pragma("unroll") for (int _i = 0; _i < 2; ++_i) \
;         __builtin_amdgcn_global_load_lds((const unsigned*)((const char*)(gbase) + (voff)[_i]), (LAS unsigned*)(lds + (bufoff) + ldsw + _i * 8192), 16, 0, 0); } while (0)
; #define PG8_LDA(dst, b, h) do { _Pragma("unroll") for (int m = 0; m < 4; ++m) _Pragma("unroll") for (int k = 0; k < 2; ++k) dst[m][k] = *(const LAS bf16x8*)(lds + PG8_SA(b, h) + aoff + m * 2048 + k * 1024); } while (0)
; #define PG8_LDB(dst, b, h) do { _Pragma("unroll") for (int n = 0; n < 2; ++n) _Pragma("unroll") for (int k = 0; k < 2; ++k) dst[n][k] = *(const LAS bf16x8*)(lds + PG8_SB(b, h) + boff + n * 2048 + k * 1024); } while (0)
; #define PG8_MMA(ai, bj, At, Bt) do { __builtin_amdgcn_s_setprio(1); _Pragma("unroll") for (int m = 0; m < 4; ++m) _Pragma("unroll") for (int n = 0; n < 2; ++n) _Pragma("unroll") for (int k = 0; k < 2; ++k) \
;         acc[ai][bj][m][n] = __builtin_amdgcn_mfma_f32_16x16x32_bf16(Bt[n][k], At[m][k], acc[ai][bj][m][n], 0, 0, 0); __builtin_amdgcn_s_setprio(0); } while (0)
; #define PG8_WAIT_V(n) asm volatile("s_waitcnt vmcnt(" #n ")" ::: "memory")
; #define PG8_WAIT_L(n) asm volatile("s_waitcnt lgkmcnt(" #n ")" ::: "memory")
; #define PG8_BAR __builtin_amdgcn_s_barrier()
; #define PG8_SCHED __builtin_amdgcn_sched_barrier(0)
; template <class Epi, class Sched, bool ALIGN_EPI = false, bool SP2 = false>
; __device__ __forceinline__ void gemm_phase(LAS unsigned char* lds, const Gemm g, const Sched& S, const Epi& E) {
;     ...
;             PG8_WAIT_V(8); PG8_WAIT_L(0); PG8_BAR; PG8_MMA(1, 0, At, B0); PG8_MMA(1, 1, At, B1); PG8_BAR; PG8_SCHED;
;             PG8_LDB(B0, 1, 0); PG8_LDB(B1, 1, 1); PG8_SCHED; PG8_LDA(At, 1, 0); PG8_STAGE(PG8_SA(0, 1), a2 + hstepA, voffA);
;             PG8_WAIT_V(8); PG8_WAIT_L(0); PG8_BAR; PG8_MMA(0, 0, At, B0); PG8_MMA(0, 1, At, B1); PG8_BAR; PG8_SCHED;
	s_setprio 1
	v_mfma_f32_16x16x32_bf16 v[62:65], v[148:151], v[182:185], v[62:65]
	v_mfma_f32_16x16x32_bf16 v[58:61], v[158:161], v[182:185], v[58:61]
	v_mfma_f32_16x16x32_bf16 v[54:57], v[148:151], v[190:193], v[54:57]
	v_mfma_f32_16x16x32_bf16 v[46:49], v[158:161], v[190:193], v[46:49]
	v_mfma_f32_16x16x32_bf16 v[38:41], v[148:151], v[198:201], v[38:41]
	v_mfma_f32_16x16x32_bf16 v[30:33], v[158:161], v[198:201], v[30:33]
	v_mfma_f32_16x16x32_bf16 v[22:25], v[148:151], v[206:209], v[22:25]
	v_mfma_f32_16x16x32_bf16 v[14:17], v[158:161], v[206:209], v[14:17]
	v_mfma_f32_16x16x32_bf16 v[62:65], v[154:157], v[186:189], v[62:65]
	v_mfma_f32_16x16x32_bf16 v[58:61], v[162:165], v[186:189], v[58:61]
	v_mfma_f32_16x16x32_bf16 v[54:57], v[154:157], v[194:197], v[54:57]
	v_mfma_f32_16x16x32_bf16 v[46:49], v[162:165], v[194:197], v[46:49]
	v_mfma_f32_16x16x32_bf16 v[38:41], v[154:157], v[202:205], v[38:41]
	v_mfma_f32_16x16x32_bf16 v[30:33], v[162:165], v[202:205], v[30:33]
	v_mfma_f32_16x16x32_bf16 v[22:25], v[154:157], v[210:213], v[22:25]
	v_mfma_f32_16x16x32_bf16 v[14:17], v[162:165], v[210:213], v[14:17]
	s_setprio 0
	s_setprio 1
	v_mfma_f32_16x16x32_bf16 v[50:53], v[166:169], v[182:185], v[50:53]
	v_mfma_f32_16x16x32_bf16 v[42:45], v[174:177], v[182:185], v[42:45]
	v_mfma_f32_16x16x32_bf16 v[34:37], v[166:169], v[190:193], v[34:37]
	v_mfma_f32_16x16x32_bf16 v[26:29], v[174:177], v[190:193], v[26:29]
	v_mfma_f32_16x16x32_bf16 v[18:21], v[166:169], v[198:201], v[18:21]
	v_mfma_f32_16x16x32_bf16 v[10:13], v[174:177], v[198:201], v[10:13]
	v_mfma_f32_16x16x32_bf16 v[6:9], v[166:169], v[206:209], v[6:9]
	v_mfma_f32_16x16x32_bf16 v[2:5], v[174:177], v[206:209], v[2:5]
	v_mfma_f32_16x16x32_bf16 v[50:53], v[170:173], v[186:189], v[50:53]
	v_mfma_f32_16x16x32_bf16 v[42:45], v[178:181], v[186:189], v[42:45]
	v_mfma_f32_16x16x32_bf16 v[34:37], v[170:173], v[194:197], v[34:37]
	v_mfma_f32_16x16x32_bf16 v[26:29], v[178:181], v[194:197], v[26:29]
	v_mfma_f32_16x16x32_bf16 v[18:21], v[170:173], v[202:205], v[18:21]
	v_mfma_f32_16x16x32_bf16 v[10:13], v[178:181], v[202:205], v[10:13]
	v_mfma_f32_16x16x32_bf16 v[6:9], v[170:173], v[210:213], v[6:9]
	v_mfma_f32_16x16x32_bf16 v[2:5], v[178:181], v[210:213], v[2:5]
	s_setprio 0
	s_barrier
	ds_read_b128 v[148:151], v146
	ds_read_b128 v[154:157], v146 offset:1024
	ds_read_b128 v[158:161], v146 offset:2048
	ds_read_b128 v[162:165], v146 offset:3072
	ds_read_b128 v[166:169], v147
	ds_read_b128 v[170:173], v147 offset:1024
	ds_read_b128 v[174:177], v147 offset:2048
	ds_read_b128 v[178:181], v147 offset:3072
	s_mov_b32 m0, s47
	v_lshl_add_u64 v[222:223], s[26:27], 0, v[130:131]
	ds_read_b128 v[182:185], v144 offset:32768
	ds_read_b128 v[186:189], v144 offset:33792
	ds_read_b128 v[190:193], v144 offset:34816
	ds_read_b128 v[194:197], v144 offset:35840
	ds_read_b128 v[198:201], v144 offset:36864
	ds_read_b128 v[202:205], v144 offset:37888
	ds_read_b128 v[206:209], v144 offset:38912
	ds_read_b128 v[210:213], v144 offset:39936
	global_load_lds_dwordx4 v[222:223], off
	v_lshl_add_u64 v[222:223], s[26:27], 0, v[134:135]
	s_mov_b32 m0, s50
	s_nop 0
	global_load_lds_dwordx4 v[222:223], off
	s_waitcnt vmcnt(8)
	s_waitcnt lgkmcnt(0)
	s_barrier
	s_setprio 1
	v_mfma_f32_16x16x32_bf16 v[126:129], v[148:151], v[182:185], v[126:129]
	v_mfma_f32_16x16x32_bf16 v[122:125], v[158:161], v[182:185], v[122:125]
	v_mfma_f32_16x16x32_bf16 v[118:121], v[148:151], v[190:193], v[118:121]
	v_mfma_f32_16x16x32_bf16 v[110:113], v[158:161], v[190:193], v[110:113]
	v_mfma_f32_16x16x32_bf16 v[102:105], v[148:151], v[198:201], v[102:105]
	v_mfma_f32_16x16x32_bf16 v[94:97], v[158:161], v[198:201], v[94:97]
	v_mfma_f32_16x16x32_bf16 v[86:89], v[148:151], v[206:209], v[86:89]
	v_mfma_f32_16x16x32_bf16 v[78:81], v[158:161], v[206:209], v[78:81]
	v_mfma_f32_16x16x32_bf16 v[126:129], v[154:157], v[186:189], v[126:129]
	v_mfma_f32_16x16x32_bf16 v[122:125], v[162:165], v[186:189], v[122:125]
	v_mfma_f32_16x16x32_bf16 v[118:121], v[154:157], v[194:197], v[118:121]
	v_mfma_f32_16x16x32_bf16 v[110:113], v[162:165], v[194:197], v[110:113]
	v_mfma_f32_16x16x32_bf16 v[102:105], v[154:157], v[202:205], v[102:105]
	v_mfma_f32_16x16x32_bf16 v[94:97], v[162:165], v[202:205], v[94:97]
	v_mfma_f32_16x16x32_bf16 v[86:89], v[154:157], v[210:213], v[86:89]
	v_mfma_f32_16x16x32_bf16 v[78:81], v[162:165], v[210:213], v[78:81]
	s_setprio 0
	s_setprio 1
	v_mfma_f32_16x16x32_bf16 v[114:117], v[166:169], v[182:185], v[114:117]
	v_mfma_f32_16x16x32_bf16 v[106:109], v[174:177], v[182:185], v[106:109]
	v_mfma_f32_16x16x32_bf16 v[98:101], v[166:169], v[190:193], v[98:101]
	v_mfma_f32_16x16x32_bf16 v[90:93], v[174:177], v[190:193], v[90:93]
	v_mfma_f32_16x16x32_bf16 v[82:85], v[166:169], v[198:201], v[82:85]
	v_mfma_f32_16x16x32_bf16 v[74:77], v[174:177], v[198:201], v[74:77]
	v_mfma_f32_16x16x32_bf16 v[70:73], v[166:169], v[206:209], v[70:73]
	v_mfma_f32_16x16x32_bf16 v[66:69], v[174:177], v[206:209], v[66:69]
	v_mfma_f32_16x16x32_bf16 v[114:117], v[170:173], v[186:189], v[114:117]
	v_mfma_f32_16x16x32_bf16 v[106:109], v[178:181], v[186:189], v[106:109]
	v_mfma_f32_16x16x32_bf16 v[98:101], v[170:173], v[194:197], v[98:101]
	v_mfma_f32_16x16x32_bf16 v[90:93], v[178:181], v[194:197], v[90:93]
	v_mfma_f32_16x16x32_bf16 v[82:85], v[170:173], v[202:205], v[82:85]
	v_mfma_f32_16x16x32_bf16 v[74:77], v[178:181], v[202:205], v[74:77]
	v_mfma_f32_16x16x32_bf16 v[70:73], v[170:173], v[210:213], v[70:73]
	v_mfma_f32_16x16x32_bf16 v[66:69], v[178:181], v[210:213], v[66:69]
	s_setprio 0
	s_barrier
; #define PG8_STAGE(bufoff, gbase, voff) do { _Pragma("unroll") for (int _i = 0; _i < 2; ++_i) \
;         __builtin_amdgcn_global_load_lds((const unsigned*)((const char*)(gbase) + (voff)[_i]), (LAS unsigned*)(lds + (bufoff) + ldsw + _i * 8192), 16, 0, 0); } while (0)
; #define PG8_LDA(dst, b, h) do { _Pragma("unroll") for (int m = 0; m < 4; ++m) _Pragma("unroll") for (int k = 0; k < 2; ++k) dst[m][k] = *(const LAS bf16x8*)(lds + PG8_SA(b, h) + aoff + m * 2048 + k * 1024); } while (0)
; #define PG8_MMA(ai, bj, At, Bt) do { __builtin_amdgcn_s_setprio(1); _Pragma("unroll") for (int m = 0; m < 4; ++m) _Pragma("unroll") for (int n = 0; n < 2; ++n) _Pragma("unroll") for (int k = 0; k < 2; ++k) \
;         acc[ai][bj][m][n] = __builtin_amdgcn_mfma_f32_16x16x32_bf16(Bt[n][k], At[m][k], acc[ai][bj][m][n], 0, 0, 0); __builtin_amdgcn_s_setprio(0); } while (0)
; #define PG8_WAIT_V(n) asm volatile("s_waitcnt vmcnt(" #n ")" ::: "memory")
; #define PG8_WAIT_L(n) asm volatile("s_waitcnt lgkmcnt(" #n ")" ::: "memory")
; #define PG8_BAR __builtin_amdgcn_s_barrier()
; #define PG8_SCHED __builtin_amdgcn_sched_barrier(0)
; template <class Epi, class Sched, bool ALIGN_EPI = false, bool SP2 = false>
; __device__ __forceinline__ void gemm_phase(LAS unsigned char* lds, const Gemm g, const Sched& S, const Epi& E) {
;     ...
;             PG8_LDA(At, 1, 1); PG8_STAGE(PG8_SB(1, 0), b3, voffB); PG8_STAGE(PG8_SB(1, 1), b3 + hstepB, voffB); PG8_STAGE(PG8_SA(1, 0), a3, voffA);
;             PG8_WAIT_V(8); PG8_WAIT_L(0); PG8_BAR; PG8_MMA(1, 0, At, B0); PG8_MMA(1, 1, At, B1); PG8_BAR; PG8_SCHED;
	s_mov_b32 m0, s71
	v_lshl_add_u64 v[214:215], v[214:215], 0, s[12:13]
	ds_read_b128 v[182:185], v144 offset:49152
	ds_read_b128 v[186:189], v144 offset:50176
	ds_read_b128 v[190:193], v144 offset:51200
	ds_read_b128 v[194:197], v144 offset:52224
	ds_read_b128 v[198:201], v144 offset:53248
	ds_read_b128 v[202:205], v144 offset:54272
	ds_read_b128 v[206:209], v144 offset:55296
	ds_read_b128 v[210:213], v144 offset:56320
	global_load_lds_dwordx4 v[214:215], off
	v_lshl_add_u64 v[214:215], v[216:217], 0, s[12:13]
	s_mov_b32 m0, s67
	s_nop 0
	global_load_lds_dwordx4 v[214:215], off
	v_lshl_add_u64 v[214:215], s[24:25], 0, v[132:133]
	s_mov_b32 m0, s70
	s_nop 0
	global_load_lds_dwordx4 v[214:215], off
	v_lshl_add_u64 v[214:215], s[24:25], 0, v[136:137]
	s_mov_b32 m0, s66
	s_nop 0
	global_load_lds_dwordx4 v[214:215], off
	v_lshl_add_u64 v[214:215], v[218:219], 0, s[12:13]
	s_mov_b32 m0, s51
	s_nop 0
	global_load_lds_dwordx4 v[214:215], off
	v_lshl_add_u64 v[214:215], v[220:221], 0, s[12:13]
	s_mov_b32 m0, s52
	s_nop 0
	global_load_lds_dwordx4 v[214:215], off
	s_waitcnt vmcnt(8)
	s_waitcnt lgkmcnt(0)
	s_barrier
	s_setprio 1
	v_mfma_f32_16x16x32_bf16 v[62:65], v[148:151], v[182:185], v[62:65]
	v_mfma_f32_16x16x32_bf16 v[58:61], v[158:161], v[182:185], v[58:61]
	v_mfma_f32_16x16x32_bf16 v[54:57], v[148:151], v[190:193], v[54:57]
	v_mfma_f32_16x16x32_bf16 v[46:49], v[158:161], v[190:193], v[46:49]
	v_mfma_f32_16x16x32_bf16 v[38:41], v[148:151], v[198:201], v[38:41]
	v_mfma_f32_16x16x32_bf16 v[30:33], v[158:161], v[198:201], v[30:33]
	v_mfma_f32_16x16x32_bf16 v[22:25], v[148:151], v[206:209], v[22:25]
	v_mfma_f32_16x16x32_bf16 v[14:17], v[158:161], v[206:209], v[14:17]
	v_mfma_f32_16x16x32_bf16 v[62:65], v[154:157], v[186:189], v[62:65]
	v_mfma_f32_16x16x32_bf16 v[58:61], v[162:165], v[186:189], v[58:61]
	v_mfma_f32_16x16x32_bf16 v[54:57], v[154:157], v[194:197], v[54:57]
	v_mfma_f32_16x16x32_bf16 v[46:49], v[162:165], v[194:197], v[46:49]
	v_mfma_f32_16x16x32_bf16 v[38:41], v[154:157], v[202:205], v[38:41]
	v_mfma_f32_16x16x32_bf16 v[30:33], v[162:165], v[202:205], v[30:33]
	v_mfma_f32_16x16x32_bf16 v[22:25], v[154:157], v[210:213], v[22:25]
	v_mfma_f32_16x16x32_bf16 v[14:17], v[162:165], v[210:213], v[14:17]
	s_setprio 0
	s_setprio 1
	v_mfma_f32_16x16x32_bf16 v[50:53], v[166:169], v[182:185], v[50:53]
	v_mfma_f32_16x16x32_bf16 v[42:45], v[174:177], v[182:185], v[42:45]
	v_mfma_f32_16x16x32_bf16 v[34:37], v[166:169], v[190:193], v[34:37]
	v_mfma_f32_16x16x32_bf16 v[26:29], v[174:177], v[190:193], v[26:29]
	v_mfma_f32_16x16x32_bf16 v[18:21], v[166:169], v[198:201], v[18:21]
	v_mfma_f32_16x16x32_bf16 v[10:13], v[174:177], v[198:201], v[10:13]
	v_mfma_f32_16x16x32_bf16 v[6:9], v[166:169], v[206:209], v[6:9]
	v_mfma_f32_16x16x32_bf16 v[2:5], v[174:177], v[206:209], v[2:5]
	v_mfma_f32_16x16x32_bf16 v[50:53], v[170:173], v[186:189], v[50:53]
	v_mfma_f32_16x16x32_bf16 v[42:45], v[178:181], v[186:189], v[42:45]
	v_mfma_f32_16x16x32_bf16 v[34:37], v[170:173], v[194:197], v[34:37]
	v_mfma_f32_16x16x32_bf16 v[26:29], v[178:181], v[194:197], v[26:29]
	v_mfma_f32_16x16x32_bf16 v[18:21], v[170:173], v[202:205], v[18:21]
	v_mfma_f32_16x16x32_bf16 v[10:13], v[178:181], v[202:205], v[10:13]
	v_mfma_f32_16x16x32_bf16 v[6:9], v[170:173], v[210:213], v[6:9]
	v_mfma_f32_16x16x32_bf16 v[2:5], v[178:181], v[210:213], v[2:5]
	s_setprio 0
	s_barrier
	s_movk_i32 s26, 0x100
	s_andn2_b64 vcc, exec, s[22:23]
	s_mov_b64 s[24:25], -1
	s_mov_b64 s[22:23], 0
	s_cbranch_vccz .LBB0_588
	s_and_b64 vcc, exec, s[14:15]
	s_cbranch_vccz .LBB0_591
	s_barrier

; #define PG8_STAGE(bufoff, gbase, voff) do { _Pragma("unroll") for (int _i = 0; _i < 2; ++_i) \
;         __builtin_amdgcn_global_load_lds((const unsigned*)((const char*)(gbase) + (voff)[_i]), (LAS unsigned*)(lds + (bufoff) + ldsw + _i * 8192), 16, 0, 0); } while (0)
; #define PG8_LDA(dst, b, h) do { _Pragma("unroll") for (int m = 0; m < 4; ++m) _Pragma("unroll") for (int k = 0; k < 2; ++k) dst[m][k] = *(const LAS bf16x8*)(lds + PG8_SA(b, h) + aoff + m * 2048 + k * 1024); } while (0)
; #define PG8_LDB(dst, b, h) do { _Pragma("unroll") for (int n = 0; n < 2; ++n) _Pragma("unroll") for (int k = 0; k < 2; ++k) dst[n][k] = *(const LAS bf16x8*)(lds + PG8_SB(b, h) + boff + n * 2048 + k * 1024); } while (0)
; #define PG8_MMA(ai, bj, At, Bt) do { __builtin_amdgcn_s_setprio(1); _Pragma("unroll") for (int m = 0; m < 4; ++m) _Pragma("unroll") for (int n = 0; n < 2; ++n) _Pragma("unroll") for (int k = 0; k < 2; ++k) \
;         acc[ai][bj][m][n] = __builtin_amdgcn_mfma_f32_16x16x32_bf16(Bt[n][k], At[m][k], acc[ai][bj][m][n], 0, 0, 0); __builtin_amdgcn_s_setprio(0); } while (0)
; #define PG8_WAIT_V(n) asm volatile("s_waitcnt vmcnt(" #n ")" ::: "memory")
; #define PG8_WAIT_L(n) asm volatile("s_waitcnt lgkmcnt(" #n ")" ::: "memory")
; #define PG8_BAR __builtin_amdgcn_s_barrier()
; #define PG8_SCHED __builtin_amdgcn_sched_barrier(0)
; template <class Epi, class Sched, bool ALIGN_EPI = false, bool SP2 = false>
; __device__ __forceinline__ void gemm_phase(LAS unsigned char* lds, const Gemm g, const Sched& S, const Epi& E) {
;     ...
;             const bool last = (t == nt - 2);
;             const char* a1 = cA + (size_t)(t + 1) * kstep;
;             const char* a2 = last ? nA : cA + (size_t)(t + 2) * kstep; const char* b2 = last ? nB : cB + (size_t)(t + 2) * kstep;
;             const char* a3 = a2 + kstep; const char* b3 = b2 + kstep;
;             if (last && has_next) S.a_ready(nxt);
;             if constexpr (SP2) {
;             PG8_LDB(B0, 0, 0); PG8_LDB(B1, 0, 1); PG8_SCHED; PG8_LDA(At, 0, 0); PG8_STAGE(PG8_SA(1, 1), a1 + hstepA, voffA);
;             PG8_WAIT_V(8); PG8_WAIT_L(0); PG8_BAR; PG8_MMA(0, 0, At, B0); PG8_MMA(0, 1, At, B1); PG8_BAR; PG8_SCHED;
;             PG8_LDA(At, 0, 1); PG8_STAGE(PG8_SB(0, 0), b2, voffB); PG8_STAGE(PG8_SB(0, 1), b2 + hstepB, voffB); PG8_STAGE(PG8_SA(0, 0), a2, voffA);
.LBB0_968:
	ds_read_b128 v[120:123], v221
	ds_read_b128 v[124:127], v221 offset:1024
	ds_read_b128 v[136:139], v221 offset:2048
	ds_read_b128 v[140:143], v221 offset:3072
	ds_read_b128 v[144:147], v222
	ds_read_b128 v[148:151], v222 offset:1024
	ds_read_b128 v[170:173], v222 offset:2048
	ds_read_b128 v[174:177], v222 offset:3072
	s_add_u32 s28, s26, 0xfff80080
	s_addc_u32 s29, s27, -1
	s_cmp_eq_u32 s50, 28
	s_cselect_b32 s31, s17, s29
	s_cselect_b32 s30, s23, s28
	s_cselect_b32 s29, s15, s49
	s_cselect_b32 s28, s25, s33
	v_lshl_add_u64 v[210:211], s[26:27], 0, v[162:163]
	s_add_i32 m0, s35, 0xc000
	ds_read_b128 v[178:181], v223
	ds_read_b128 v[182:185], v223 offset:1024
	ds_read_b128 v[186:189], v223 offset:2048
	ds_read_b128 v[190:193], v223 offset:3072
	ds_read_b128 v[194:197], v223 offset:4096
	ds_read_b128 v[198:201], v223 offset:5120
	ds_read_b128 v[202:205], v223 offset:6144
	ds_read_b128 v[206:209], v223 offset:7168
	global_load_lds_dwordx4 v[210:211], off
	v_lshl_add_u64 v[210:211], s[26:27], 0, v[164:165]
	s_add_i32 m0, s35, 0xe000
	s_nop 0
	global_load_lds_dwordx4 v[210:211], off
	s_waitcnt vmcnt(8)
	s_waitcnt lgkmcnt(0)
	s_barrier
	s_setprio 1
	v_mfma_f32_16x16x32_bf16 v[132:135], v[120:123], v[178:181], v[132:135]
	v_mfma_f32_16x16x32_bf16 v[128:131], v[136:139], v[178:181], v[128:131]
	v_mfma_f32_16x16x32_bf16 v[100:103], v[120:123], v[186:189], v[100:103]
	v_mfma_f32_16x16x32_bf16 v[96:99], v[136:139], v[186:189], v[96:99]
	v_mfma_f32_16x16x32_bf16 v[116:119], v[120:123], v[194:197], v[116:119]
	v_mfma_f32_16x16x32_bf16 v[112:115], v[136:139], v[194:197], v[112:115]
	v_mfma_f32_16x16x32_bf16 v[108:111], v[120:123], v[202:205], v[108:111]
	v_mfma_f32_16x16x32_bf16 v[104:107], v[136:139], v[202:205], v[104:107]
	v_mfma_f32_16x16x32_bf16 v[132:135], v[124:127], v[182:185], v[132:135]
	v_mfma_f32_16x16x32_bf16 v[128:131], v[140:143], v[182:185], v[128:131]
	v_mfma_f32_16x16x32_bf16 v[100:103], v[124:127], v[190:193], v[100:103]
	v_mfma_f32_16x16x32_bf16 v[96:99], v[140:143], v[190:193], v[96:99]
	v_mfma_f32_16x16x32_bf16 v[116:119], v[124:127], v[198:201], v[116:119]
	v_mfma_f32_16x16x32_bf16 v[112:115], v[140:143], v[198:201], v[112:115]
	v_mfma_f32_16x16x32_bf16 v[108:111], v[124:127], v[206:209], v[108:111]
	v_mfma_f32_16x16x32_bf16 v[104:107], v[140:143], v[206:209], v[104:107]
	s_setprio 0
	s_setprio 1
	v_mfma_f32_16x16x32_bf16 v[60:63], v[144:147], v[178:181], v[60:63]
	v_mfma_f32_16x16x32_bf16 v[56:59], v[170:173], v[178:181], v[56:59]
	v_mfma_f32_16x16x32_bf16 v[52:55], v[144:147], v[186:189], v[52:55]
	v_mfma_f32_16x16x32_bf16 v[48:51], v[170:173], v[186:189], v[48:51]
	v_mfma_f32_16x16x32_bf16 v[44:47], v[144:147], v[194:197], v[44:47]
	v_mfma_f32_16x16x32_bf16 v[40:43], v[170:173], v[194:197], v[40:43]
	v_mfma_f32_16x16x32_bf16 v[36:39], v[144:147], v[202:205], v[36:39]
	v_mfma_f32_16x16x32_bf16 v[32:35], v[170:173], v[202:205], v[32:35]
	v_mfma_f32_16x16x32_bf16 v[60:63], v[148:151], v[182:185], v[60:63]
	v_mfma_f32_16x16x32_bf16 v[56:59], v[174:177], v[182:185], v[56:59]
	v_mfma_f32_16x16x32_bf16 v[52:55], v[148:151], v[190:193], v[52:55]
	v_mfma_f32_16x16x32_bf16 v[48:51], v[174:177], v[190:193], v[48:51]
	v_mfma_f32_16x16x32_bf16 v[44:47], v[148:151], v[198:201], v[44:47]
	v_mfma_f32_16x16x32_bf16 v[40:43], v[174:177], v[198:201], v[40:43]
	v_mfma_f32_16x16x32_bf16 v[36:39], v[148:151], v[206:209], v[36:39]
	v_mfma_f32_16x16x32_bf16 v[32:35], v[174:177], v[206:209], v[32:35]
	s_setprio 0
	s_barrier
	s_add_i32 s51, s45, s34
	v_lshl_add_u64 v[210:211], s[28:29], 0, v[156:157]
	s_mov_b32 m0, s51
	ds_read_b128 v[178:181], v223 offset:16384
	ds_read_b128 v[182:185], v223 offset:17408
	ds_read_b128 v[186:189], v223 offset:18432
	ds_read_b128 v[190:193], v223 offset:19456
	ds_read_b128 v[194:197], v223 offset:20480
	ds_read_b128 v[198:201], v223 offset:21504
	ds_read_b128 v[202:205], v223 offset:22528
	ds_read_b128 v[206:209], v223 offset:23552
	global_load_lds_dwordx4 v[210:211], off
	s_add_i32 m0, s51, 0x2000
	s_add_u32 s52, s28, 0x80000
	v_lshl_add_u64 v[212:213], s[28:29], 0, v[160:161]
	s_addc_u32 s53, s29, 0
	s_add_i32 s51, s46, s34
	global_load_lds_dwordx4 v[212:213], off
	v_lshl_add_u64 v[214:215], s[52:53], 0, v[156:157]
	s_mov_b32 m0, s51
	v_lshl_add_u64 v[216:217], s[30:31], 0, v[158:159]
	global_load_lds_dwordx4 v[214:215], off
	v_lshl_add_u64 v[214:215], s[52:53], 0, v[160:161]
	s_add_i32 m0, s51, 0x2000
	s_nop 0
	global_load_lds_dwordx4 v[214:215], off
	v_lshl_add_u64 v[214:215], s[30:31], 0, v[154:155]
	s_mov_b32 m0, s35
	s_nop 0
	global_load_lds_dwordx4 v[214:215], off
	s_mov_b32 m0, s36
	s_nop 0
	global_load_lds_dwordx4 v[216:217], off
	s_waitcnt vmcnt(8)
	s_waitcnt lgkmcnt(0)
	s_barrier
; #define PG8_STAGE(bufoff, gbase, voff) do { _Pragma("unroll") for (int _i = 0; _i < 2; ++_i) \
;         __builtin_amdgcn_global_load_lds((const unsigned*)((const char*)(gbase) + (voff)[_i]), (LAS unsigned*)(lds + (bufoff) + ldsw + _i * 8192), 16, 0, 0); } while (0)
; #define PG8_LDA(dst, b, h) do { _Pragma("unroll") for (int m = 0; m < 4; ++m) _Pragma("unroll") for (int k = 0; k < 2; ++k) dst[m][k] = *(const LAS bf16x8*)(lds + PG8_SA(b, h) + aoff + m * 2048 + k * 1024); } while (0)
; #define PG8_LDB(dst, b, h) do { _Pragma("unroll") for (int n = 0; n < 2; ++n) _Pragma("unroll") for (int k = 0; k < 2; ++k) dst[n][k] = *(const LAS bf16x8*)(lds + PG8_SB(b, h) + boff + n * 2048 + k * 1024); } while (0)
; #define PG8_MMA(ai, bj, At, Bt) do { __builtin_amdgcn_s_setprio(1); _Pragma("unroll") for (int m = 0; m < 4; ++m) _Pragma("unroll") for (int n = 0; n < 2; ++n) _Pragma("unroll") for (int k = 0; k < 2; ++k) \
;         acc[ai][bj][m][n] = __builtin_amdgcn_mfma_f32_16x16x32_bf16(Bt[n][k], At[m][k], acc[ai][bj][m][n], 0, 0, 0); __builtin_amdgcn_s_setprio(0); } while (0)
; #define PG8_WAIT_V(n) asm volatile("s_waitcnt vmcnt(" #n ")" ::: "memory")
; #define PG8_WAIT_L(n) asm volatile("s_waitcnt lgkmcnt(" #n ")" ::: "memory")
; #define PG8_BAR __builtin_amdgcn_s_barrier()
; #define PG8_SCHED __builtin_amdgcn_sched_barrier(0)
; template <class Epi, class Sched, bool ALIGN_EPI = false, bool SP2 = false>
; __device__ __forceinline__ void gemm_phase(LAS unsigned char* lds, const Gemm g, const Sched& S, const Epi& E) {
;     ...
;             PG8_WAIT_V(8); PG8_WAIT_L(0); PG8_BAR; PG8_MMA(1, 0, At, B0); PG8_MMA(1, 1, At, B1); PG8_BAR; PG8_SCHED;
;             PG8_LDB(B0, 1, 0); PG8_LDB(B1, 1, 1); PG8_SCHED; PG8_LDA(At, 1, 0); PG8_STAGE(PG8_SA(0, 1), a2 + hstepA, voffA);
;             PG8_WAIT_V(8); PG8_WAIT_L(0); PG8_BAR; PG8_MMA(0, 0, At, B0); PG8_MMA(0, 1, At, B1); PG8_BAR; PG8_SCHED;
	s_setprio 1
	v_mfma_f32_16x16x32_bf16 v[92:95], v[120:123], v[178:181], v[92:95]
	v_mfma_f32_16x16x32_bf16 v[88:91], v[136:139], v[178:181], v[88:91]
	v_mfma_f32_16x16x32_bf16 v[84:87], v[120:123], v[186:189], v[84:87]
	v_mfma_f32_16x16x32_bf16 v[80:83], v[136:139], v[186:189], v[80:83]
	v_mfma_f32_16x16x32_bf16 v[76:79], v[120:123], v[194:197], v[76:79]
	v_mfma_f32_16x16x32_bf16 v[72:75], v[136:139], v[194:197], v[72:75]
	v_mfma_f32_16x16x32_bf16 v[68:71], v[120:123], v[202:205], v[68:71]
	v_mfma_f32_16x16x32_bf16 v[64:67], v[136:139], v[202:205], v[64:67]
	v_mfma_f32_16x16x32_bf16 v[92:95], v[124:127], v[182:185], v[92:95]
	v_mfma_f32_16x16x32_bf16 v[88:91], v[140:143], v[182:185], v[88:91]
	v_mfma_f32_16x16x32_bf16 v[84:87], v[124:127], v[190:193], v[84:87]
	v_mfma_f32_16x16x32_bf16 v[80:83], v[140:143], v[190:193], v[80:83]
	v_mfma_f32_16x16x32_bf16 v[76:79], v[124:127], v[198:201], v[76:79]
	v_mfma_f32_16x16x32_bf16 v[72:75], v[140:143], v[198:201], v[72:75]
	v_mfma_f32_16x16x32_bf16 v[68:71], v[124:127], v[206:209], v[68:71]
	v_mfma_f32_16x16x32_bf16 v[64:67], v[140:143], v[206:209], v[64:67]
	s_setprio 0
	s_setprio 1
	v_mfma_f32_16x16x32_bf16 v[28:31], v[144:147], v[178:181], v[28:31]
	v_mfma_f32_16x16x32_bf16 v[24:27], v[170:173], v[178:181], v[24:27]
	v_mfma_f32_16x16x32_bf16 v[20:23], v[144:147], v[186:189], v[20:23]
	v_mfma_f32_16x16x32_bf16 v[16:19], v[170:173], v[186:189], v[16:19]
	v_mfma_f32_16x16x32_bf16 v[12:15], v[144:147], v[194:197], v[12:15]
	v_mfma_f32_16x16x32_bf16 v[8:11], v[170:173], v[194:197], v[8:11]
	v_mfma_f32_16x16x32_bf16 v[4:7], v[144:147], v[202:205], v[4:7]
	v_mfma_f32_16x16x32_bf16 v[0:3], v[170:173], v[202:205], v[0:3]
	v_mfma_f32_16x16x32_bf16 v[28:31], v[148:151], v[182:185], v[28:31]
	v_mfma_f32_16x16x32_bf16 v[24:27], v[174:177], v[182:185], v[24:27]
	v_mfma_f32_16x16x32_bf16 v[20:23], v[148:151], v[190:193], v[20:23]
	v_mfma_f32_16x16x32_bf16 v[16:19], v[174:177], v[190:193], v[16:19]
	v_mfma_f32_16x16x32_bf16 v[12:15], v[148:151], v[198:201], v[12:15]
	v_mfma_f32_16x16x32_bf16 v[8:11], v[174:177], v[198:201], v[8:11]
	v_mfma_f32_16x16x32_bf16 v[4:7], v[148:151], v[206:209], v[4:7]
	v_mfma_f32_16x16x32_bf16 v[0:3], v[174:177], v[206:209], v[0:3]
	s_setprio 0
	s_barrier
	ds_read_b128 v[120:123], v225
	ds_read_b128 v[124:127], v225 offset:1024
	ds_read_b128 v[136:139], v225 offset:2048
	ds_read_b128 v[140:143], v225 offset:3072
	ds_read_b128 v[144:147], v226
	ds_read_b128 v[148:151], v226 offset:1024
	ds_read_b128 v[170:173], v226 offset:2048
	ds_read_b128 v[174:177], v226 offset:3072
	s_add_u32 s30, s30, 0x80000
	s_addc_u32 s31, s31, 0
	s_mov_b32 m0, s37
	v_lshl_add_u64 v[218:219], s[30:31], 0, v[154:155]
	ds_read_b128 v[178:181], v223 offset:32768
	ds_read_b128 v[182:185], v223 offset:33792
	ds_read_b128 v[186:189], v223 offset:34816
	ds_read_b128 v[190:193], v223 offset:35840
	ds_read_b128 v[194:197], v223 offset:36864
	ds_read_b128 v[198:201], v223 offset:37888
	ds_read_b128 v[202:205], v223 offset:38912
	ds_read_b128 v[206:209], v223 offset:39936
	global_load_lds_dwordx4 v[218:219], off
	v_lshl_add_u64 v[218:219], s[30:31], 0, v[158:159]
	s_mov_b32 m0, s38
	s_nop 0
	global_load_lds_dwordx4 v[218:219], off
	s_waitcnt vmcnt(8)
	s_waitcnt lgkmcnt(0)
	s_barrier
	s_setprio 1
	v_mfma_f32_16x16x32_bf16 v[132:135], v[120:123], v[178:181], v[132:135]
	v_mfma_f32_16x16x32_bf16 v[128:131], v[136:139], v[178:181], v[128:131]
	v_mfma_f32_16x16x32_bf16 v[100:103], v[120:123], v[186:189], v[100:103]
	v_mfma_f32_16x16x32_bf16 v[96:99], v[136:139], v[186:189], v[96:99]
	v_mfma_f32_16x16x32_bf16 v[116:119], v[120:123], v[194:197], v[116:119]
	v_mfma_f32_16x16x32_bf16 v[112:115], v[136:139], v[194:197], v[112:115]
	v_mfma_f32_16x16x32_bf16 v[108:111], v[120:123], v[202:205], v[108:111]
	v_mfma_f32_16x16x32_bf16 v[104:107], v[136:139], v[202:205], v[104:107]
	v_mfma_f32_16x16x32_bf16 v[132:135], v[124:127], v[182:185], v[132:135]
	v_mfma_f32_16x16x32_bf16 v[128:131], v[140:143], v[182:185], v[128:131]
	v_mfma_f32_16x16x32_bf16 v[100:103], v[124:127], v[190:193], v[100:103]
	v_mfma_f32_16x16x32_bf16 v[96:99], v[140:143], v[190:193], v[96:99]
	v_mfma_f32_16x16x32_bf16 v[116:119], v[124:127], v[198:201], v[116:119]
	v_mfma_f32_16x16x32_bf16 v[112:115], v[140:143], v[198:201], v[112:115]
	v_mfma_f32_16x16x32_bf16 v[108:111], v[124:127], v[206:209], v[108:111]
	v_mfma_f32_16x16x32_bf16 v[104:107], v[140:143], v[206:209], v[104:107]
	s_setprio 0
	s_setprio 1
	v_mfma_f32_16x16x32_bf16 v[60:63], v[144:147], v[178:181], v[60:63]
	v_mfma_f32_16x16x32_bf16 v[56:59], v[170:173], v[178:181], v[56:59]
	v_mfma_f32_16x16x32_bf16 v[52:55], v[144:147], v[186:189], v[52:55]
	v_mfma_f32_16x16x32_bf16 v[48:51], v[170:173], v[186:189], v[48:51]
	v_mfma_f32_16x16x32_bf16 v[44:47], v[144:147], v[194:197], v[44:47]
	v_mfma_f32_16x16x32_bf16 v[40:43], v[170:173], v[194:197], v[40:43]
	v_mfma_f32_16x16x32_bf16 v[36:39], v[144:147], v[202:205], v[36:39]
	v_mfma_f32_16x16x32_bf16 v[32:35], v[170:173], v[202:205], v[32:35]
	v_mfma_f32_16x16x32_bf16 v[60:63], v[148:151], v[182:185], v[60:63]
	v_mfma_f32_16x16x32_bf16 v[56:59], v[174:177], v[182:185], v[56:59]
	v_mfma_f32_16x16x32_bf16 v[52:55], v[148:151], v[190:193], v[52:55]
	v_mfma_f32_16x16x32_bf16 v[48:51], v[174:177], v[190:193], v[48:51]
	v_mfma_f32_16x16x32_bf16 v[44:47], v[148:151], v[198:201], v[44:47]
	v_mfma_f32_16x16x32_bf16 v[40:43], v[174:177], v[198:201], v[40:43]
	v_mfma_f32_16x16x32_bf16 v[36:39], v[148:151], v[206:209], v[36:39]
	v_mfma_f32_16x16x32_bf16 v[32:35], v[174:177], v[206:209], v[32:35]
	s_setprio 0
	s_barrier
; #define PG8_STAGE(bufoff, gbase, voff) do { _Pragma("unroll") for (int _i = 0; _i < 2; ++_i) \
;         __builtin_amdgcn_global_load_lds((const unsigned*)((const char*)(gbase) + (voff)[_i]), (LAS unsigned*)(lds + (bufoff) + ldsw + _i * 8192), 16, 0, 0); } while (0)
; #define PG8_LDA(dst, b, h) do { _Pragma("unroll") for (int m = 0; m < 4; ++m) _Pragma("unroll") for (int k = 0; k < 2; ++k) dst[m][k] = *(const LAS bf16x8*)(lds + PG8_SA(b, h) + aoff + m * 2048 + k * 1024); } while (0)
; #define PG8_MMA(ai, bj, At, Bt) do { __builtin_amdgcn_s_setprio(1); _Pragma("unroll") for (int m = 0; m < 4; ++m) _Pragma("unroll") for (int n = 0; n < 2; ++n) _Pragma("unroll") for (int k = 0; k < 2; ++k) \
;         acc[ai][bj][m][n] = __builtin_amdgcn_mfma_f32_16x16x32_bf16(Bt[n][k], At[m][k], acc[ai][bj][m][n], 0, 0, 0); __builtin_amdgcn_s_setprio(0); } while (0)
; #define PG8_WAIT_V(n) asm volatile("s_waitcnt vmcnt(" #n ")" ::: "memory")
; #define PG8_WAIT_L(n) asm volatile("s_waitcnt lgkmcnt(" #n ")" ::: "memory")
; #define PG8_BAR __builtin_amdgcn_s_barrier()
; #define PG8_SCHED __builtin_amdgcn_sched_barrier(0)
; template <class Epi, class Sched, bool ALIGN_EPI = false, bool SP2 = false>
; __device__ __forceinline__ void gemm_phase(LAS unsigned char* lds, const Gemm g, const Sched& S, const Epi& E) {
;     ...
;         for (int t = 0; t < nt; t += 2) {
;             const bool last = (t == nt - 2);
;     ...
;             PG8_LDA(At, 1, 1); PG8_STAGE(PG8_SB(1, 0), b3, voffB); PG8_STAGE(PG8_SB(1, 1), b3 + hstepB, voffB); PG8_STAGE(PG8_SA(1, 0), a3, voffA);
;             PG8_WAIT_V(8); PG8_WAIT_L(0); PG8_BAR; PG8_MMA(1, 0, At, B0); PG8_MMA(1, 1, At, B1); PG8_BAR; PG8_SCHED;
	s_add_i32 s30, s47, s34
	v_lshl_add_u64 v[210:211], v[210:211], 0, s[10:11]
	s_mov_b32 m0, s30
	ds_read_b128 v[178:181], v223 offset:49152
	ds_read_b128 v[182:185], v223 offset:50176
	ds_read_b128 v[186:189], v223 offset:51200
	ds_read_b128 v[190:193], v223 offset:52224
	ds_read_b128 v[194:197], v223 offset:53248
	ds_read_b128 v[198:201], v223 offset:54272
	ds_read_b128 v[202:205], v223 offset:55296
	ds_read_b128 v[206:209], v223 offset:56320
	global_load_lds_dwordx4 v[210:211], off
	s_add_i32 m0, s30, 0x2000
	s_add_u32 s28, s28, 0x80080
	v_lshl_add_u64 v[210:211], v[212:213], 0, s[10:11]
	s_addc_u32 s29, s29, 0
	s_add_i32 s30, s48, s34
	global_load_lds_dwordx4 v[210:211], off
	v_lshl_add_u64 v[210:211], s[28:29], 0, v[156:157]
	s_mov_b32 m0, s30
	s_nop 0
	global_load_lds_dwordx4 v[210:211], off
	v_lshl_add_u64 v[210:211], s[28:29], 0, v[160:161]
	s_add_i32 m0, s30, 0x2000
	s_nop 0
	global_load_lds_dwordx4 v[210:211], off
	v_lshl_add_u64 v[210:211], v[214:215], 0, s[10:11]
	s_mov_b32 m0, s39
	s_nop 0
	global_load_lds_dwordx4 v[210:211], off
	v_lshl_add_u64 v[210:211], v[216:217], 0, s[10:11]
	s_mov_b32 m0, s40
	s_nop 0
	global_load_lds_dwordx4 v[210:211], off
	s_waitcnt vmcnt(8)
	s_waitcnt lgkmcnt(0)
	s_barrier
	s_setprio 1
	v_mfma_f32_16x16x32_bf16 v[92:95], v[120:123], v[178:181], v[92:95]
	v_mfma_f32_16x16x32_bf16 v[88:91], v[136:139], v[178:181], v[88:91]
	v_mfma_f32_16x16x32_bf16 v[84:87], v[120:123], v[186:189], v[84:87]
	v_mfma_f32_16x16x32_bf16 v[80:83], v[136:139], v[186:189], v[80:83]
	v_mfma_f32_16x16x32_bf16 v[76:79], v[120:123], v[194:197], v[76:79]
	v_mfma_f32_16x16x32_bf16 v[72:75], v[136:139], v[194:197], v[72:75]
	v_mfma_f32_16x16x32_bf16 v[68:71], v[120:123], v[202:205], v[68:71]
	v_mfma_f32_16x16x32_bf16 v[64:67], v[136:139], v[202:205], v[64:67]
	v_mfma_f32_16x16x32_bf16 v[92:95], v[124:127], v[182:185], v[92:95]
	v_mfma_f32_16x16x32_bf16 v[88:91], v[140:143], v[182:185], v[88:91]
	v_mfma_f32_16x16x32_bf16 v[84:87], v[124:127], v[190:193], v[84:87]
	v_mfma_f32_16x16x32_bf16 v[80:83], v[140:143], v[190:193], v[80:83]
	v_mfma_f32_16x16x32_bf16 v[76:79], v[124:127], v[198:201], v[76:79]
	v_mfma_f32_16x16x32_bf16 v[72:75], v[140:143], v[198:201], v[72:75]
	v_mfma_f32_16x16x32_bf16 v[68:71], v[124:127], v[206:209], v[68:71]
	v_mfma_f32_16x16x32_bf16 v[64:67], v[140:143], v[206:209], v[64:67]
	s_setprio 0
	s_setprio 1
	v_mfma_f32_16x16x32_bf16 v[28:31], v[144:147], v[178:181], v[28:31]
	v_mfma_f32_16x16x32_bf16 v[24:27], v[170:173], v[178:181], v[24:27]
	v_mfma_f32_16x16x32_bf16 v[20:23], v[144:147], v[186:189], v[20:23]
	v_mfma_f32_16x16x32_bf16 v[16:19], v[170:173], v[186:189], v[16:19]
	v_mfma_f32_16x16x32_bf16 v[12:15], v[144:147], v[194:197], v[12:15]
	v_mfma_f32_16x16x32_bf16 v[8:11], v[170:173], v[194:197], v[8:11]
	v_mfma_f32_16x16x32_bf16 v[4:7], v[144:147], v[202:205], v[4:7]
	v_mfma_f32_16x16x32_bf16 v[0:3], v[170:173], v[202:205], v[0:3]
	v_mfma_f32_16x16x32_bf16 v[28:31], v[148:151], v[182:185], v[28:31]
	v_mfma_f32_16x16x32_bf16 v[24:27], v[174:177], v[182:185], v[24:27]
	v_mfma_f32_16x16x32_bf16 v[20:23], v[148:151], v[190:193], v[20:23]
	v_mfma_f32_16x16x32_bf16 v[16:19], v[174:177], v[190:193], v[16:19]
	v_mfma_f32_16x16x32_bf16 v[12:15], v[148:151], v[198:201], v[12:15]
	v_mfma_f32_16x16x32_bf16 v[8:11], v[174:177], v[198:201], v[8:11]
	v_mfma_f32_16x16x32_bf16 v[4:7], v[148:151], v[206:209], v[4:7]
	v_mfma_f32_16x16x32_bf16 v[0:3], v[174:177], v[206:209], v[0:3]
	s_setprio 0
	s_barrier
	s_add_i32 s50, s50, 2
	s_add_u32 s26, s26, 0x100
	s_addc_u32 s27, s27, 0
	s_add_u32 s33, s33, 0x100
	s_addc_u32 s49, s49, 0
	s_cmp_gt_u32 s50, 29
	s_cbranch_scc0 .LBB0_968
	s_and_b64 vcc, exec, s[12:13]
	s_cbranch_vccz .LBB0_971
	s_barrier

; #define PG8_STAGE(bufoff, gbase, voff) do { _Pragma("unroll") for (int _i = 0; _i < 2; ++_i) \
;         __builtin_amdgcn_global_load_lds((const unsigned*)((const char*)(gbase) + (voff)[_i]), (LAS unsigned*)(lds + (bufoff) + ldsw + _i * 8192), 16, 0, 0); } while (0)
; #define PG8_LDA(dst, b, h) do { _Pragma("unroll") for (int m = 0; m < 4; ++m) _Pragma("unroll") for (int k = 0; k < 2; ++k) dst[m][k] = *(const LAS bf16x8*)(lds + PG8_SA(b, h) + aoff + m * 2048 + k * 1024); } while (0)
; #define PG8_LDB(dst, b, h) do { _Pragma("unroll") for (int n = 0; n < 2; ++n) _Pragma("unroll") for (int k = 0; k < 2; ++k) dst[n][k] = *(const LAS bf16x8*)(lds + PG8_SB(b, h) + boff + n * 2048 + k * 1024); } while (0)
; #define PG8_MMA(ai, bj, At, Bt) do { __builtin_amdgcn_s_setprio(1); _Pragma("unroll") for (int m = 0; m < 4; ++m) _Pragma("unroll") for (int n = 0; n < 2; ++n) _Pragma("unroll") for (int k = 0; k < 2; ++k) \
;         acc[ai][bj][m][n] = __builtin_amdgcn_mfma_f32_16x16x32_bf16(Bt[n][k], At[m][k], acc[ai][bj][m][n], 0, 0, 0); __builtin_amdgcn_s_setprio(0); } while (0)
; #define PG8_WAIT_V(n) asm volatile("s_waitcnt vmcnt(" #n ")" ::: "memory")
; #define PG8_WAIT_L(n) asm volatile("s_waitcnt lgkmcnt(" #n ")" ::: "memory")
; #define PG8_BAR __builtin_amdgcn_s_barrier()
; #define PG8_SCHED __builtin_amdgcn_sched_barrier(0)
; template <class Epi, class Sched, bool ALIGN_EPI = false, bool SP2 = false>
; __device__ __forceinline__ void gemm_phase(LAS unsigned char* lds, const Gemm g, const Sched& S, const Epi& E) {
;     ...
;             const bool last = (t == nt - 2);
;             const char* a1 = cA + (size_t)(t + 1) * kstep;
;             const char* a2 = last ? nA : cA + (size_t)(t + 2) * kstep; const char* b2 = last ? nB : cB + (size_t)(t + 2) * kstep;
;             const char* a3 = a2 + kstep; const char* b3 = b2 + kstep;
;             if (last && has_next) S.a_ready(nxt);
;             if constexpr (SP2) {
;             PG8_LDB(B0, 0, 0); PG8_LDB(B1, 0, 1); PG8_SCHED; PG8_LDA(At, 0, 0); PG8_STAGE(PG8_SA(1, 1), a1 + hstepA, voffA);
;             PG8_WAIT_V(8); PG8_WAIT_L(0); PG8_BAR; PG8_MMA(0, 0, At, B0); PG8_MMA(0, 1, At, B1); PG8_BAR; PG8_SCHED;
;             PG8_LDA(At, 0, 1); PG8_STAGE(PG8_SB(0, 0), b2, voffB); PG8_STAGE(PG8_SB(0, 1), b2 + hstepB, voffB); PG8_STAGE(PG8_SA(0, 0), a2, voffA);
.LBB0_1055:
	ds_read_b128 v[80:83], v171
	ds_read_b128 v[88:91], v171 offset:1024
	ds_read_b128 v[92:95], v171 offset:2048
	ds_read_b128 v[96:99], v171 offset:3072
	ds_read_b128 v[162:165], v172
	ds_read_b128 v[166:169], v172 offset:1024
	ds_read_b128 v[178:181], v172 offset:2048
	ds_read_b128 v[182:185], v172 offset:3072
	s_add_u32 s26, s24, 0xfff80080
	s_addc_u32 s27, s25, -1
	s_cmp_eq_u32 s53, 28
	s_cselect_b32 s29, s17, s27
	s_cselect_b32 s28, s49, s26
	s_cselect_b32 s27, s15, s52
	s_cselect_b32 s26, s50, s51
	v_lshl_add_u64 v[218:219], s[24:25], 0, v[154:155]
	s_add_i32 m0, s23, 0xc000
	ds_read_b128 v[186:189], v173
	ds_read_b128 v[190:193], v173 offset:1024
	ds_read_b128 v[194:197], v173 offset:2048
	ds_read_b128 v[198:201], v173 offset:3072
	ds_read_b128 v[202:205], v173 offset:4096
	ds_read_b128 v[206:209], v173 offset:5120
	ds_read_b128 v[210:213], v173 offset:6144
	ds_read_b128 v[214:217], v173 offset:7168
	global_load_lds_dwordx4 v[218:219], off
	v_lshl_add_u64 v[218:219], s[24:25], 0, v[156:157]
	s_add_i32 m0, s23, 0xe000
	s_nop 0
	global_load_lds_dwordx4 v[218:219], off
	s_waitcnt vmcnt(8)
	s_waitcnt lgkmcnt(0)
	s_barrier
	s_setprio 1
	v_mfma_f32_16x16x32_bf16 v[140:143], v[80:83], v[186:189], v[140:143]
	v_mfma_f32_16x16x32_bf16 v[136:139], v[92:95], v[186:189], v[136:139]
	v_mfma_f32_16x16x32_bf16 v[124:127], v[80:83], v[194:197], v[124:127]
	v_mfma_f32_16x16x32_bf16 v[120:123], v[92:95], v[194:197], v[120:123]
	v_mfma_f32_16x16x32_bf16 v[108:111], v[80:83], v[202:205], v[108:111]
	v_mfma_f32_16x16x32_bf16 v[104:107], v[92:95], v[202:205], v[104:107]
	v_mfma_f32_16x16x32_bf16 v[76:79], v[80:83], v[210:213], v[76:79]
	v_mfma_f32_16x16x32_bf16 v[72:75], v[92:95], v[210:213], v[72:75]
	v_mfma_f32_16x16x32_bf16 v[140:143], v[88:91], v[190:193], v[140:143]
	v_mfma_f32_16x16x32_bf16 v[136:139], v[96:99], v[190:193], v[136:139]
	v_mfma_f32_16x16x32_bf16 v[124:127], v[88:91], v[198:201], v[124:127]
	v_mfma_f32_16x16x32_bf16 v[120:123], v[96:99], v[198:201], v[120:123]
	v_mfma_f32_16x16x32_bf16 v[108:111], v[88:91], v[206:209], v[108:111]
	v_mfma_f32_16x16x32_bf16 v[104:107], v[96:99], v[206:209], v[104:107]
	v_mfma_f32_16x16x32_bf16 v[76:79], v[88:91], v[214:217], v[76:79]
	v_mfma_f32_16x16x32_bf16 v[72:75], v[96:99], v[214:217], v[72:75]
	s_setprio 0
	s_setprio 1
	v_mfma_f32_16x16x32_bf16 v[132:135], v[162:165], v[186:189], v[132:135]
	v_mfma_f32_16x16x32_bf16 v[128:131], v[178:181], v[186:189], v[128:131]
	v_mfma_f32_16x16x32_bf16 v[116:119], v[162:165], v[194:197], v[116:119]
	v_mfma_f32_16x16x32_bf16 v[112:115], v[178:181], v[194:197], v[112:115]
	v_mfma_f32_16x16x32_bf16 v[100:103], v[162:165], v[202:205], v[100:103]
	v_mfma_f32_16x16x32_bf16 v[84:87], v[178:181], v[202:205], v[84:87]
	v_mfma_f32_16x16x32_bf16 v[68:71], v[162:165], v[210:213], v[68:71]
	v_mfma_f32_16x16x32_bf16 v[64:67], v[178:181], v[210:213], v[64:67]
	v_mfma_f32_16x16x32_bf16 v[132:135], v[166:169], v[190:193], v[132:135]
	v_mfma_f32_16x16x32_bf16 v[128:131], v[182:185], v[190:193], v[128:131]
	v_mfma_f32_16x16x32_bf16 v[116:119], v[166:169], v[198:201], v[116:119]
	v_mfma_f32_16x16x32_bf16 v[112:115], v[182:185], v[198:201], v[112:115]
	v_mfma_f32_16x16x32_bf16 v[100:103], v[166:169], v[206:209], v[100:103]
	v_mfma_f32_16x16x32_bf16 v[84:87], v[182:185], v[206:209], v[84:87]
	v_mfma_f32_16x16x32_bf16 v[68:71], v[166:169], v[214:217], v[68:71]
	v_mfma_f32_16x16x32_bf16 v[64:67], v[182:185], v[214:217], v[64:67]
	s_setprio 0
	s_barrier
	s_add_i32 s54, s43, s30
	v_lshl_add_u64 v[218:219], s[26:27], 0, v[146:147]
	s_mov_b32 m0, s54
	ds_read_b128 v[186:189], v173 offset:16384
	ds_read_b128 v[190:193], v173 offset:17408
	ds_read_b128 v[194:197], v173 offset:18432
	ds_read_b128 v[198:201], v173 offset:19456
	ds_read_b128 v[202:205], v173 offset:20480
	ds_read_b128 v[206:209], v173 offset:21504
	ds_read_b128 v[210:213], v173 offset:22528
	ds_read_b128 v[214:217], v173 offset:23552
	global_load_lds_dwordx4 v[218:219], off
	s_add_i32 m0, s54, 0x2000
	s_add_u32 s54, s26, 0x80000
	v_lshl_add_u64 v[220:221], s[26:27], 0, v[150:151]
	s_addc_u32 s55, s27, 0
	s_add_i32 s56, s44, s30
	global_load_lds_dwordx4 v[220:221], off
	v_lshl_add_u64 v[222:223], s[54:55], 0, v[146:147]
	s_mov_b32 m0, s56
	v_lshl_add_u64 v[224:225], s[28:29], 0, v[148:149]
	global_load_lds_dwordx4 v[222:223], off
	v_lshl_add_u64 v[222:223], s[54:55], 0, v[150:151]
	s_add_i32 m0, s56, 0x2000
	s_nop 0
	global_load_lds_dwordx4 v[222:223], off
	v_lshl_add_u64 v[222:223], s[28:29], 0, v[144:145]
	s_mov_b32 m0, s23
	s_nop 0
	global_load_lds_dwordx4 v[222:223], off
	s_mov_b32 m0, s35
	s_nop 0
	global_load_lds_dwordx4 v[224:225], off
	s_waitcnt vmcnt(8)
	s_waitcnt lgkmcnt(0)
	s_barrier
; #define PG8_STAGE(bufoff, gbase, voff) do { _Pragma("unroll") for (int _i = 0; _i < 2; ++_i) \
;         __builtin_amdgcn_global_load_lds((const unsigned*)((const char*)(gbase) + (voff)[_i]), (LAS unsigned*)(lds + (bufoff) + ldsw + _i * 8192), 16, 0, 0); } while (0)
; #define PG8_LDA(dst, b, h) do { _Pragma("unroll") for (int m = 0; m < 4; ++m) _Pragma("unroll") for (int k = 0; k < 2; ++k) dst[m][k] = *(const LAS bf16x8*)(lds + PG8_SA(b, h) + aoff + m * 2048 + k * 1024); } while (0)
; #define PG8_LDB(dst, b, h) do { _Pragma("unroll") for (int n = 0; n < 2; ++n) _Pragma("unroll") for (int k = 0; k < 2; ++k) dst[n][k] = *(const LAS bf16x8*)(lds + PG8_SB(b, h) + boff + n * 2048 + k * 1024); } while (0)
; #define PG8_MMA(ai, bj, At, Bt) do { __builtin_amdgcn_s_setprio(1); _Pragma("unroll") for (int m = 0; m < 4; ++m) _Pragma("unroll") for (int n = 0; n < 2; ++n) _Pragma("unroll") for (int k = 0; k < 2; ++k) \
;         acc[ai][bj][m][n] = __builtin_amdgcn_mfma_f32_16x16x32_bf16(Bt[n][k], At[m][k], acc[ai][bj][m][n], 0, 0, 0); __builtin_amdgcn_s_setprio(0); } while (0)
; #define PG8_WAIT_V(n) asm volatile("s_waitcnt vmcnt(" #n ")" ::: "memory")
; #define PG8_WAIT_L(n) asm volatile("s_waitcnt lgkmcnt(" #n ")" ::: "memory")
; #define PG8_BAR __builtin_amdgcn_s_barrier()
; #define PG8_SCHED __builtin_amdgcn_sched_barrier(0)
; template <class Epi, class Sched, bool ALIGN_EPI = false, bool SP2 = false>
; __device__ __forceinline__ void gemm_phase(LAS unsigned char* lds, const Gemm g, const Sched& S, const Epi& E) {
;     ...
;             PG8_WAIT_V(8); PG8_WAIT_L(0); PG8_BAR; PG8_MMA(1, 0, At, B0); PG8_MMA(1, 1, At, B1); PG8_BAR; PG8_SCHED;
;             PG8_LDB(B0, 1, 0); PG8_LDB(B1, 1, 1); PG8_SCHED; PG8_LDA(At, 1, 0); PG8_STAGE(PG8_SA(0, 1), a2 + hstepA, voffA);
;             PG8_WAIT_V(8); PG8_WAIT_L(0); PG8_BAR; PG8_MMA(0, 0, At, B0); PG8_MMA(0, 1, At, B1); PG8_BAR; PG8_SCHED;
	s_setprio 1
	v_mfma_f32_16x16x32_bf16 v[60:63], v[80:83], v[186:189], v[60:63]
	v_mfma_f32_16x16x32_bf16 v[56:59], v[92:95], v[186:189], v[56:59]
	v_mfma_f32_16x16x32_bf16 v[44:47], v[80:83], v[194:197], v[44:47]
	v_mfma_f32_16x16x32_bf16 v[40:43], v[92:95], v[194:197], v[40:43]
	v_mfma_f32_16x16x32_bf16 v[28:31], v[80:83], v[202:205], v[28:31]
	v_mfma_f32_16x16x32_bf16 v[24:27], v[92:95], v[202:205], v[24:27]
	v_mfma_f32_16x16x32_bf16 v[12:15], v[80:83], v[210:213], v[12:15]
	v_mfma_f32_16x16x32_bf16 v[8:11], v[92:95], v[210:213], v[8:11]
	v_mfma_f32_16x16x32_bf16 v[60:63], v[88:91], v[190:193], v[60:63]
	v_mfma_f32_16x16x32_bf16 v[56:59], v[96:99], v[190:193], v[56:59]
	v_mfma_f32_16x16x32_bf16 v[44:47], v[88:91], v[198:201], v[44:47]
	v_mfma_f32_16x16x32_bf16 v[40:43], v[96:99], v[198:201], v[40:43]
	v_mfma_f32_16x16x32_bf16 v[28:31], v[88:91], v[206:209], v[28:31]
	v_mfma_f32_16x16x32_bf16 v[24:27], v[96:99], v[206:209], v[24:27]
	v_mfma_f32_16x16x32_bf16 v[12:15], v[88:91], v[214:217], v[12:15]
	v_mfma_f32_16x16x32_bf16 v[8:11], v[96:99], v[214:217], v[8:11]
	s_setprio 0
	s_setprio 1
	v_mfma_f32_16x16x32_bf16 v[52:55], v[162:165], v[186:189], v[52:55]
	v_mfma_f32_16x16x32_bf16 v[48:51], v[178:181], v[186:189], v[48:51]
	v_mfma_f32_16x16x32_bf16 v[36:39], v[162:165], v[194:197], v[36:39]
	v_mfma_f32_16x16x32_bf16 v[32:35], v[178:181], v[194:197], v[32:35]
	v_mfma_f32_16x16x32_bf16 v[20:23], v[162:165], v[202:205], v[20:23]
	v_mfma_f32_16x16x32_bf16 v[16:19], v[178:181], v[202:205], v[16:19]
	v_mfma_f32_16x16x32_bf16 v[4:7], v[162:165], v[210:213], v[4:7]
	v_mfma_f32_16x16x32_bf16 v[0:3], v[178:181], v[210:213], v[0:3]
	v_mfma_f32_16x16x32_bf16 v[52:55], v[166:169], v[190:193], v[52:55]
	v_mfma_f32_16x16x32_bf16 v[48:51], v[182:185], v[190:193], v[48:51]
	v_mfma_f32_16x16x32_bf16 v[36:39], v[166:169], v[198:201], v[36:39]
	v_mfma_f32_16x16x32_bf16 v[32:35], v[182:185], v[198:201], v[32:35]
	v_mfma_f32_16x16x32_bf16 v[20:23], v[166:169], v[206:209], v[20:23]
	v_mfma_f32_16x16x32_bf16 v[16:19], v[182:185], v[206:209], v[16:19]
	v_mfma_f32_16x16x32_bf16 v[4:7], v[166:169], v[214:217], v[4:7]
	v_mfma_f32_16x16x32_bf16 v[0:3], v[182:185], v[214:217], v[0:3]
	s_setprio 0
	s_barrier
	ds_read_b128 v[80:83], v175
	ds_read_b128 v[88:91], v175 offset:1024
	ds_read_b128 v[92:95], v175 offset:2048
	ds_read_b128 v[96:99], v175 offset:3072
	ds_read_b128 v[162:165], v176
	ds_read_b128 v[166:169], v176 offset:1024
	ds_read_b128 v[178:181], v176 offset:2048
	ds_read_b128 v[182:185], v176 offset:3072
	s_add_u32 s28, s28, 0x80000
	s_addc_u32 s29, s29, 0
	s_mov_b32 m0, s36
	v_lshl_add_u64 v[226:227], s[28:29], 0, v[144:145]
	ds_read_b128 v[186:189], v173 offset:32768
	ds_read_b128 v[190:193], v173 offset:33792
	ds_read_b128 v[194:197], v173 offset:34816
	ds_read_b128 v[198:201], v173 offset:35840
	ds_read_b128 v[202:205], v173 offset:36864
	ds_read_b128 v[206:209], v173 offset:37888
	ds_read_b128 v[210:213], v173 offset:38912
	ds_read_b128 v[214:217], v173 offset:39936
	global_load_lds_dwordx4 v[226:227], off
	v_lshl_add_u64 v[226:227], s[28:29], 0, v[148:149]
	s_mov_b32 m0, s37
	s_nop 0
	global_load_lds_dwordx4 v[226:227], off
	s_waitcnt vmcnt(8)
	s_waitcnt lgkmcnt(0)
	s_barrier
	s_setprio 1
	v_mfma_f32_16x16x32_bf16 v[140:143], v[80:83], v[186:189], v[140:143]
	v_mfma_f32_16x16x32_bf16 v[136:139], v[92:95], v[186:189], v[136:139]
	v_mfma_f32_16x16x32_bf16 v[124:127], v[80:83], v[194:197], v[124:127]
	v_mfma_f32_16x16x32_bf16 v[120:123], v[92:95], v[194:197], v[120:123]
	v_mfma_f32_16x16x32_bf16 v[108:111], v[80:83], v[202:205], v[108:111]
	v_mfma_f32_16x16x32_bf16 v[104:107], v[92:95], v[202:205], v[104:107]
	v_mfma_f32_16x16x32_bf16 v[76:79], v[80:83], v[210:213], v[76:79]
	v_mfma_f32_16x16x32_bf16 v[72:75], v[92:95], v[210:213], v[72:75]
	v_mfma_f32_16x16x32_bf16 v[140:143], v[88:91], v[190:193], v[140:143]
	v_mfma_f32_16x16x32_bf16 v[136:139], v[96:99], v[190:193], v[136:139]
	v_mfma_f32_16x16x32_bf16 v[124:127], v[88:91], v[198:201], v[124:127]
	v_mfma_f32_16x16x32_bf16 v[120:123], v[96:99], v[198:201], v[120:123]
	v_mfma_f32_16x16x32_bf16 v[108:111], v[88:91], v[206:209], v[108:111]
	v_mfma_f32_16x16x32_bf16 v[104:107], v[96:99], v[206:209], v[104:107]
	v_mfma_f32_16x16x32_bf16 v[76:79], v[88:91], v[214:217], v[76:79]
	v_mfma_f32_16x16x32_bf16 v[72:75], v[96:99], v[214:217], v[72:75]
	s_setprio 0
	s_setprio 1
	v_mfma_f32_16x16x32_bf16 v[132:135], v[162:165], v[186:189], v[132:135]
	v_mfma_f32_16x16x32_bf16 v[128:131], v[178:181], v[186:189], v[128:131]
	v_mfma_f32_16x16x32_bf16 v[116:119], v[162:165], v[194:197], v[116:119]
	v_mfma_f32_16x16x32_bf16 v[112:115], v[178:181], v[194:197], v[112:115]
	v_mfma_f32_16x16x32_bf16 v[100:103], v[162:165], v[202:205], v[100:103]
	v_mfma_f32_16x16x32_bf16 v[84:87], v[178:181], v[202:205], v[84:87]
	v_mfma_f32_16x16x32_bf16 v[68:71], v[162:165], v[210:213], v[68:71]
	v_mfma_f32_16x16x32_bf16 v[64:67], v[178:181], v[210:213], v[64:67]
	v_mfma_f32_16x16x32_bf16 v[132:135], v[166:169], v[190:193], v[132:135]
	v_mfma_f32_16x16x32_bf16 v[128:131], v[182:185], v[190:193], v[128:131]
	v_mfma_f32_16x16x32_bf16 v[116:119], v[166:169], v[198:201], v[116:119]
	v_mfma_f32_16x16x32_bf16 v[112:115], v[182:185], v[198:201], v[112:115]
	v_mfma_f32_16x16x32_bf16 v[100:103], v[166:169], v[206:209], v[100:103]
	v_mfma_f32_16x16x32_bf16 v[84:87], v[182:185], v[206:209], v[84:87]
	v_mfma_f32_16x16x32_bf16 v[68:71], v[166:169], v[214:217], v[68:71]
	v_mfma_f32_16x16x32_bf16 v[64:67], v[182:185], v[214:217], v[64:67]
	s_setprio 0
	s_barrier
; #define PG8_STAGE(bufoff, gbase, voff) do { _Pragma("unroll") for (int _i = 0; _i < 2; ++_i) \
;         __builtin_amdgcn_global_load_lds((const unsigned*)((const char*)(gbase) + (voff)[_i]), (LAS unsigned*)(lds + (bufoff) + ldsw + _i * 8192), 16, 0, 0); } while (0)
; #define PG8_LDA(dst, b, h) do { _Pragma("unroll") for (int m = 0; m < 4; ++m) _Pragma("unroll") for (int k = 0; k < 2; ++k) dst[m][k] = *(const LAS bf16x8*)(lds + PG8_SA(b, h) + aoff + m * 2048 + k * 1024); } while (0)
; #define PG8_MMA(ai, bj, At, Bt) do { __builtin_amdgcn_s_setprio(1); _Pragma("unroll") for (int m = 0; m < 4; ++m) _Pragma("unroll") for (int n = 0; n < 2; ++n) _Pragma("unroll") for (int k = 0; k < 2; ++k) \
;         acc[ai][bj][m][n] = __builtin_amdgcn_mfma_f32_16x16x32_bf16(Bt[n][k], At[m][k], acc[ai][bj][m][n], 0, 0, 0); __builtin_amdgcn_s_setprio(0); } while (0)
; #define PG8_WAIT_V(n) asm volatile("s_waitcnt vmcnt(" #n ")" ::: "memory")
; #define PG8_WAIT_L(n) asm volatile("s_waitcnt lgkmcnt(" #n ")" ::: "memory")
; #define PG8_BAR __builtin_amdgcn_s_barrier()
; #define PG8_SCHED __builtin_amdgcn_sched_barrier(0)
; template <class Epi, class Sched, bool ALIGN_EPI = false, bool SP2 = false>
; __device__ __forceinline__ void gemm_phase(LAS unsigned char* lds, const Gemm g, const Sched& S, const Epi& E) {
;     ...
;         for (int t = 0; t < nt; t += 2) {
;             const bool last = (t == nt - 2);
;     ...
;             PG8_LDA(At, 1, 1); PG8_STAGE(PG8_SB(1, 0), b3, voffB); PG8_STAGE(PG8_SB(1, 1), b3 + hstepB, voffB); PG8_STAGE(PG8_SA(1, 0), a3, voffA);
;             PG8_WAIT_V(8); PG8_WAIT_L(0); PG8_BAR; PG8_MMA(1, 0, At, B0); PG8_MMA(1, 1, At, B1); PG8_BAR; PG8_SCHED;
	s_add_i32 s28, s47, s30
	v_lshl_add_u64 v[218:219], v[218:219], 0, s[8:9]
	s_mov_b32 m0, s28
	ds_read_b128 v[186:189], v173 offset:49152
	ds_read_b128 v[190:193], v173 offset:50176
	ds_read_b128 v[194:197], v173 offset:51200
	ds_read_b128 v[198:201], v173 offset:52224
	ds_read_b128 v[202:205], v173 offset:53248
	ds_read_b128 v[206:209], v173 offset:54272
	ds_read_b128 v[210:213], v173 offset:55296
	ds_read_b128 v[214:217], v173 offset:56320
	global_load_lds_dwordx4 v[218:219], off
	s_add_i32 m0, s28, 0x2000
	s_add_u32 s26, s26, 0x80080
	v_lshl_add_u64 v[218:219], v[220:221], 0, s[8:9]
	s_addc_u32 s27, s27, 0
	s_add_i32 s28, s48, s30
	global_load_lds_dwordx4 v[218:219], off
	v_lshl_add_u64 v[218:219], s[26:27], 0, v[146:147]
	s_mov_b32 m0, s28
	s_nop 0
	global_load_lds_dwordx4 v[218:219], off
	v_lshl_add_u64 v[218:219], s[26:27], 0, v[150:151]
	s_add_i32 m0, s28, 0x2000
	s_nop 0
	global_load_lds_dwordx4 v[218:219], off
	v_lshl_add_u64 v[218:219], v[222:223], 0, s[8:9]
	s_mov_b32 m0, s40
	s_nop 0
	global_load_lds_dwordx4 v[218:219], off
	v_lshl_add_u64 v[218:219], v[224:225], 0, s[8:9]
	s_mov_b32 m0, s41
	s_nop 0
	global_load_lds_dwordx4 v[218:219], off
	s_waitcnt vmcnt(8)
	s_waitcnt lgkmcnt(0)
	s_barrier
	s_setprio 1
	v_mfma_f32_16x16x32_bf16 v[60:63], v[80:83], v[186:189], v[60:63]
	v_mfma_f32_16x16x32_bf16 v[56:59], v[92:95], v[186:189], v[56:59]
	v_mfma_f32_16x16x32_bf16 v[44:47], v[80:83], v[194:197], v[44:47]
	v_mfma_f32_16x16x32_bf16 v[40:43], v[92:95], v[194:197], v[40:43]
	v_mfma_f32_16x16x32_bf16 v[28:31], v[80:83], v[202:205], v[28:31]
	v_mfma_f32_16x16x32_bf16 v[24:27], v[92:95], v[202:205], v[24:27]
	v_mfma_f32_16x16x32_bf16 v[12:15], v[80:83], v[210:213], v[12:15]
	v_mfma_f32_16x16x32_bf16 v[8:11], v[92:95], v[210:213], v[8:11]
	v_mfma_f32_16x16x32_bf16 v[60:63], v[88:91], v[190:193], v[60:63]
	v_mfma_f32_16x16x32_bf16 v[56:59], v[96:99], v[190:193], v[56:59]
	v_mfma_f32_16x16x32_bf16 v[44:47], v[88:91], v[198:201], v[44:47]
	v_mfma_f32_16x16x32_bf16 v[40:43], v[96:99], v[198:201], v[40:43]
	v_mfma_f32_16x16x32_bf16 v[28:31], v[88:91], v[206:209], v[28:31]
	v_mfma_f32_16x16x32_bf16 v[24:27], v[96:99], v[206:209], v[24:27]
	v_mfma_f32_16x16x32_bf16 v[12:15], v[88:91], v[214:217], v[12:15]
	v_mfma_f32_16x16x32_bf16 v[8:11], v[96:99], v[214:217], v[8:11]
	s_setprio 0
	s_setprio 1
	v_mfma_f32_16x16x32_bf16 v[52:55], v[162:165], v[186:189], v[52:55]
	v_mfma_f32_16x16x32_bf16 v[48:51], v[178:181], v[186:189], v[48:51]
	v_mfma_f32_16x16x32_bf16 v[36:39], v[162:165], v[194:197], v[36:39]
	v_mfma_f32_16x16x32_bf16 v[32:35], v[178:181], v[194:197], v[32:35]
	v_mfma_f32_16x16x32_bf16 v[20:23], v[162:165], v[202:205], v[20:23]
	v_mfma_f32_16x16x32_bf16 v[16:19], v[178:181], v[202:205], v[16:19]
	v_mfma_f32_16x16x32_bf16 v[4:7], v[162:165], v[210:213], v[4:7]
	v_mfma_f32_16x16x32_bf16 v[0:3], v[178:181], v[210:213], v[0:3]
	v_mfma_f32_16x16x32_bf16 v[52:55], v[166:169], v[190:193], v[52:55]
	v_mfma_f32_16x16x32_bf16 v[48:51], v[182:185], v[190:193], v[48:51]
	v_mfma_f32_16x16x32_bf16 v[36:39], v[166:169], v[198:201], v[36:39]
	v_mfma_f32_16x16x32_bf16 v[32:35], v[182:185], v[198:201], v[32:35]
	v_mfma_f32_16x16x32_bf16 v[20:23], v[166:169], v[206:209], v[20:23]
	v_mfma_f32_16x16x32_bf16 v[16:19], v[182:185], v[206:209], v[16:19]
	v_mfma_f32_16x16x32_bf16 v[4:7], v[166:169], v[214:217], v[4:7]
	v_mfma_f32_16x16x32_bf16 v[0:3], v[182:185], v[214:217], v[0:3]
	s_setprio 0
	s_barrier
	s_add_i32 s53, s53, 2
	s_add_u32 s24, s24, 0x100
	s_addc_u32 s25, s25, 0
	s_add_u32 s51, s51, 0x100
	s_addc_u32 s52, s52, 0
	s_cmp_gt_u32 s53, 29
	s_cbranch_scc0 .LBB0_1055
	s_and_b64 vcc, exec, s[10:11]
	s_cbranch_vccz .LBB0_1058
	s_barrier

; #define PG8_STAGE(bufoff, gbase, voff) do { _Pragma("unroll") for (int _i = 0; _i < 2; ++_i) \
;         __builtin_amdgcn_global_load_lds((const unsigned*)((const char*)(gbase) + (voff)[_i]), (LAS unsigned*)(lds + (bufoff) + ldsw + _i * 8192), 16, 0, 0); } while (0)
; #define PG8_LDA(dst, b, h) do { _Pragma("unroll") for (int m = 0; m < 4; ++m) _Pragma("unroll") for (int k = 0; k < 2; ++k) dst[m][k] = *(const LAS bf16x8*)(lds + PG8_SA(b, h) + aoff + m * 2048 + k * 1024); } while (0)
; #define PG8_LDB(dst, b, h) do { _Pragma("unroll") for (int n = 0; n < 2; ++n) _Pragma("unroll") for (int k = 0; k < 2; ++k) dst[n][k] = *(const LAS bf16x8*)(lds + PG8_SB(b, h) + boff + n * 2048 + k * 1024); } while (0)
; #define PG8_MMA(ai, bj, At, Bt) do { __builtin_amdgcn_s_setprio(1); _Pragma("unroll") for (int m = 0; m < 4; ++m) _Pragma("unroll") for (int n = 0; n < 2; ++n) _Pragma("unroll") for (int k = 0; k < 2; ++k) \
;         acc[ai][bj][m][n] = __builtin_amdgcn_mfma_f32_16x16x32_bf16(Bt[n][k], At[m][k], acc[ai][bj][m][n], 0, 0, 0); __builtin_amdgcn_s_setprio(0); } while (0)
; #define PG8_WAIT_V(n) asm volatile("s_waitcnt vmcnt(" #n ")" ::: "memory")
; #define PG8_WAIT_L(n) asm volatile("s_waitcnt lgkmcnt(" #n ")" ::: "memory")
; #define PG8_BAR __builtin_amdgcn_s_barrier()
; #define PG8_SCHED __builtin_amdgcn_sched_barrier(0)
; template <class Epi, class Sched, bool ALIGN_EPI = false, bool SP2 = false>
; __device__ __forceinline__ void gemm_phase(LAS unsigned char* lds, const Gemm g, const Sched& S, const Epi& E) {
;     ...
;             const bool last = (t == nt - 2);
;             const char* a1 = cA + (size_t)(t + 1) * kstep;
;             const char* a2 = last ? nA : cA + (size_t)(t + 2) * kstep; const char* b2 = last ? nB : cB + (size_t)(t + 2) * kstep;
;             const char* a3 = a2 + kstep; const char* b3 = b2 + kstep;
;             if (last && has_next) S.a_ready(nxt);
;             if constexpr (SP2) {
;             PG8_LDB(B0, 0, 0); PG8_LDB(B1, 0, 1); PG8_SCHED; PG8_LDA(At, 0, 0); PG8_STAGE(PG8_SA(1, 1), a1 + hstepA, voffA);
;             PG8_WAIT_V(8); PG8_WAIT_L(0); PG8_BAR; PG8_MMA(0, 0, At, B0); PG8_MMA(0, 1, At, B1); PG8_BAR; PG8_SCHED;
;             PG8_LDA(At, 0, 1); PG8_STAGE(PG8_SB(0, 0), b2, voffB); PG8_STAGE(PG8_SB(0, 1), b2 + hstepB, voffB); PG8_STAGE(PG8_SA(0, 0), a2, voffA);
.LBB0_1138:
	ds_read_b128 v[128:131], v176
	ds_read_b128 v[132:135], v176 offset:1024
	ds_read_b128 v[152:155], v176 offset:2048
	ds_read_b128 v[156:159], v176 offset:3072
	ds_read_b128 v[160:163], v177
	ds_read_b128 v[164:167], v177 offset:1024
	ds_read_b128 v[168:171], v177 offset:2048
	ds_read_b128 v[182:185], v177 offset:3072
	s_add_u32 s22, s20, 0xffea0080
	s_addc_u32 s23, s21, -1
	s_cmpk_eq_i32 s49, 0x54
	s_cselect_b32 s25, s3, s23
	s_cselect_b32 s24, s2, s22
	s_cselect_b32 s23, s19, s48
	s_cselect_b32 s22, s18, s47
	v_lshl_add_u64 v[172:173], s[20:21], 0, v[144:145]
	s_add_i32 m0, s28, 0xc000
	ds_read_b128 v[186:189], v178
	ds_read_b128 v[190:193], v178 offset:1024
	ds_read_b128 v[194:197], v178 offset:2048
	ds_read_b128 v[198:201], v178 offset:3072
	ds_read_b128 v[202:205], v178 offset:4096
	ds_read_b128 v[206:209], v178 offset:5120
	ds_read_b128 v[210:213], v178 offset:6144
	ds_read_b128 v[214:217], v178 offset:7168
	global_load_lds_dwordx4 v[172:173], off
	v_lshl_add_u64 v[172:173], s[20:21], 0, v[146:147]
	s_add_i32 m0, s28, 0xe000
	s_nop 0
	global_load_lds_dwordx4 v[172:173], off
	s_waitcnt vmcnt(8)
	s_waitcnt lgkmcnt(0)
	s_barrier
	s_setprio 1
	v_mfma_f32_16x16x32_bf16 v[124:127], v[128:131], v[186:189], v[124:127]
	v_mfma_f32_16x16x32_bf16 v[120:123], v[152:155], v[186:189], v[120:123]
	v_mfma_f32_16x16x32_bf16 v[116:119], v[128:131], v[194:197], v[116:119]
	v_mfma_f32_16x16x32_bf16 v[112:115], v[152:155], v[194:197], v[112:115]
	v_mfma_f32_16x16x32_bf16 v[108:111], v[128:131], v[202:205], v[108:111]
	v_mfma_f32_16x16x32_bf16 v[104:107], v[152:155], v[202:205], v[104:107]
	v_mfma_f32_16x16x32_bf16 v[100:103], v[128:131], v[210:213], v[100:103]
	v_mfma_f32_16x16x32_bf16 v[96:99], v[152:155], v[210:213], v[96:99]
	v_mfma_f32_16x16x32_bf16 v[124:127], v[132:135], v[190:193], v[124:127]
	v_mfma_f32_16x16x32_bf16 v[120:123], v[156:159], v[190:193], v[120:123]
	v_mfma_f32_16x16x32_bf16 v[116:119], v[132:135], v[198:201], v[116:119]
	v_mfma_f32_16x16x32_bf16 v[112:115], v[156:159], v[198:201], v[112:115]
	v_mfma_f32_16x16x32_bf16 v[108:111], v[132:135], v[206:209], v[108:111]
	v_mfma_f32_16x16x32_bf16 v[104:107], v[156:159], v[206:209], v[104:107]
	v_mfma_f32_16x16x32_bf16 v[100:103], v[132:135], v[214:217], v[100:103]
	v_mfma_f32_16x16x32_bf16 v[96:99], v[156:159], v[214:217], v[96:99]
	s_setprio 0
	s_setprio 1
	v_mfma_f32_16x16x32_bf16 v[68:71], v[160:163], v[186:189], v[68:71]
	v_mfma_f32_16x16x32_bf16 v[60:63], v[168:171], v[186:189], v[60:63]
	v_mfma_f32_16x16x32_bf16 v[52:55], v[160:163], v[194:197], v[52:55]
	v_mfma_f32_16x16x32_bf16 v[48:51], v[168:171], v[194:197], v[48:51]
	v_mfma_f32_16x16x32_bf16 v[44:47], v[160:163], v[202:205], v[44:47]
	v_mfma_f32_16x16x32_bf16 v[40:43], v[168:171], v[202:205], v[40:43]
	v_mfma_f32_16x16x32_bf16 v[36:39], v[160:163], v[210:213], v[36:39]
	v_mfma_f32_16x16x32_bf16 v[32:35], v[168:171], v[210:213], v[32:35]
	v_mfma_f32_16x16x32_bf16 v[68:71], v[164:167], v[190:193], v[68:71]
	v_mfma_f32_16x16x32_bf16 v[60:63], v[182:185], v[190:193], v[60:63]
	v_mfma_f32_16x16x32_bf16 v[52:55], v[164:167], v[198:201], v[52:55]
	v_mfma_f32_16x16x32_bf16 v[48:51], v[182:185], v[198:201], v[48:51]
	v_mfma_f32_16x16x32_bf16 v[44:47], v[164:167], v[206:209], v[44:47]
	v_mfma_f32_16x16x32_bf16 v[40:43], v[182:185], v[206:209], v[40:43]
	v_mfma_f32_16x16x32_bf16 v[36:39], v[164:167], v[214:217], v[36:39]
	v_mfma_f32_16x16x32_bf16 v[32:35], v[182:185], v[214:217], v[32:35]
	s_setprio 0
	s_barrier
	s_add_i32 s50, s40, s27
	v_lshl_add_u64 v[172:173], s[22:23], 0, v[138:139]
	s_mov_b32 m0, s50
	ds_read_b128 v[186:189], v178 offset:16384
	ds_read_b128 v[190:193], v178 offset:17408
	ds_read_b128 v[194:197], v178 offset:18432
	ds_read_b128 v[198:201], v178 offset:19456
	ds_read_b128 v[202:205], v178 offset:20480
	ds_read_b128 v[206:209], v178 offset:21504
	ds_read_b128 v[210:213], v178 offset:22528
	ds_read_b128 v[214:217], v178 offset:23552
	global_load_lds_dwordx4 v[172:173], off
	s_add_i32 m0, s50, 0x2000
	s_add_u32 s50, s22, 0x160000
	v_lshl_add_u64 v[218:219], s[22:23], 0, v[142:143]
	s_addc_u32 s51, s23, 0
	s_add_i32 s52, s41, s27
	global_load_lds_dwordx4 v[218:219], off
	v_lshl_add_u64 v[220:221], s[50:51], 0, v[138:139]
	s_mov_b32 m0, s52
	v_lshl_add_u64 v[222:223], s[24:25], 0, v[140:141]
	global_load_lds_dwordx4 v[220:221], off
	v_lshl_add_u64 v[220:221], s[50:51], 0, v[142:143]
	s_add_i32 m0, s52, 0x2000
	s_nop 0
	global_load_lds_dwordx4 v[220:221], off
	v_lshl_add_u64 v[220:221], s[24:25], 0, v[136:137]
	s_mov_b32 m0, s28
	s_nop 0
	global_load_lds_dwordx4 v[220:221], off
	s_mov_b32 m0, s29
	s_nop 0
	global_load_lds_dwordx4 v[222:223], off
	s_waitcnt vmcnt(8)
	s_waitcnt lgkmcnt(0)
	s_barrier
; #define PG8_STAGE(bufoff, gbase, voff) do { _Pragma("unroll") for (int _i = 0; _i < 2; ++_i) \
;         __builtin_amdgcn_global_load_lds((const unsigned*)((const char*)(gbase) + (voff)[_i]), (LAS unsigned*)(lds + (bufoff) + ldsw + _i * 8192), 16, 0, 0); } while (0)
; #define PG8_LDA(dst, b, h) do { _Pragma("unroll") for (int m = 0; m < 4; ++m) _Pragma("unroll") for (int k = 0; k < 2; ++k) dst[m][k] = *(const LAS bf16x8*)(lds + PG8_SA(b, h) + aoff + m * 2048 + k * 1024); } while (0)
; #define PG8_LDB(dst, b, h) do { _Pragma("unroll") for (int n = 0; n < 2; ++n) _Pragma("unroll") for (int k = 0; k < 2; ++k) dst[n][k] = *(const LAS bf16x8*)(lds + PG8_SB(b, h) + boff + n * 2048 + k * 1024); } while (0)
; #define PG8_MMA(ai, bj, At, Bt) do { __builtin_amdgcn_s_setprio(1); _Pragma("unroll") for (int m = 0; m < 4; ++m) _Pragma("unroll") for (int n = 0; n < 2; ++n) _Pragma("unroll") for (int k = 0; k < 2; ++k) \
;         acc[ai][bj][m][n] = __builtin_amdgcn_mfma_f32_16x16x32_bf16(Bt[n][k], At[m][k], acc[ai][bj][m][n], 0, 0, 0); __builtin_amdgcn_s_setprio(0); } while (0)
; #define PG8_WAIT_V(n) asm volatile("s_waitcnt vmcnt(" #n ")" ::: "memory")
; #define PG8_WAIT_L(n) asm volatile("s_waitcnt lgkmcnt(" #n ")" ::: "memory")
; #define PG8_BAR __builtin_amdgcn_s_barrier()
; #define PG8_SCHED __builtin_amdgcn_sched_barrier(0)
; template <class Epi, class Sched, bool ALIGN_EPI = false, bool SP2 = false>
; __device__ __forceinline__ void gemm_phase(LAS unsigned char* lds, const Gemm g, const Sched& S, const Epi& E) {
;     ...
;             PG8_WAIT_V(8); PG8_WAIT_L(0); PG8_BAR; PG8_MMA(1, 0, At, B0); PG8_MMA(1, 1, At, B1); PG8_BAR; PG8_SCHED;
;             PG8_LDB(B0, 1, 0); PG8_LDB(B1, 1, 1); PG8_SCHED; PG8_LDA(At, 1, 0); PG8_STAGE(PG8_SA(0, 1), a2 + hstepA, voffA);
;             PG8_WAIT_V(8); PG8_WAIT_L(0); PG8_BAR; PG8_MMA(0, 0, At, B0); PG8_MMA(0, 1, At, B1); PG8_BAR; PG8_SCHED;
	s_setprio 1
	v_mfma_f32_16x16x32_bf16 v[92:95], v[128:131], v[186:189], v[92:95]
	v_mfma_f32_16x16x32_bf16 v[88:91], v[152:155], v[186:189], v[88:91]
	v_mfma_f32_16x16x32_bf16 v[84:87], v[128:131], v[194:197], v[84:87]
	v_mfma_f32_16x16x32_bf16 v[80:83], v[152:155], v[194:197], v[80:83]
	v_mfma_f32_16x16x32_bf16 v[76:79], v[128:131], v[202:205], v[76:79]
	v_mfma_f32_16x16x32_bf16 v[72:75], v[152:155], v[202:205], v[72:75]
	v_mfma_f32_16x16x32_bf16 v[64:67], v[128:131], v[210:213], v[64:67]
	v_mfma_f32_16x16x32_bf16 v[56:59], v[152:155], v[210:213], v[56:59]
	v_mfma_f32_16x16x32_bf16 v[92:95], v[132:135], v[190:193], v[92:95]
	v_mfma_f32_16x16x32_bf16 v[88:91], v[156:159], v[190:193], v[88:91]
	v_mfma_f32_16x16x32_bf16 v[84:87], v[132:135], v[198:201], v[84:87]
	v_mfma_f32_16x16x32_bf16 v[80:83], v[156:159], v[198:201], v[80:83]
	v_mfma_f32_16x16x32_bf16 v[76:79], v[132:135], v[206:209], v[76:79]
	v_mfma_f32_16x16x32_bf16 v[72:75], v[156:159], v[206:209], v[72:75]
	v_mfma_f32_16x16x32_bf16 v[64:67], v[132:135], v[214:217], v[64:67]
	v_mfma_f32_16x16x32_bf16 v[56:59], v[156:159], v[214:217], v[56:59]
	s_setprio 0
	s_setprio 1
	v_mfma_f32_16x16x32_bf16 v[28:31], v[160:163], v[186:189], v[28:31]
	v_mfma_f32_16x16x32_bf16 v[24:27], v[168:171], v[186:189], v[24:27]
	v_mfma_f32_16x16x32_bf16 v[20:23], v[160:163], v[194:197], v[20:23]
	v_mfma_f32_16x16x32_bf16 v[16:19], v[168:171], v[194:197], v[16:19]
	v_mfma_f32_16x16x32_bf16 v[12:15], v[160:163], v[202:205], v[12:15]
	v_mfma_f32_16x16x32_bf16 v[8:11], v[168:171], v[202:205], v[8:11]
	v_mfma_f32_16x16x32_bf16 v[4:7], v[160:163], v[210:213], v[4:7]
	v_mfma_f32_16x16x32_bf16 v[0:3], v[168:171], v[210:213], v[0:3]
	v_mfma_f32_16x16x32_bf16 v[28:31], v[164:167], v[190:193], v[28:31]
	v_mfma_f32_16x16x32_bf16 v[24:27], v[182:185], v[190:193], v[24:27]
	v_mfma_f32_16x16x32_bf16 v[20:23], v[164:167], v[198:201], v[20:23]
	v_mfma_f32_16x16x32_bf16 v[16:19], v[182:185], v[198:201], v[16:19]
	v_mfma_f32_16x16x32_bf16 v[12:15], v[164:167], v[206:209], v[12:15]
	v_mfma_f32_16x16x32_bf16 v[8:11], v[182:185], v[206:209], v[8:11]
	v_mfma_f32_16x16x32_bf16 v[4:7], v[164:167], v[214:217], v[4:7]
	v_mfma_f32_16x16x32_bf16 v[0:3], v[182:185], v[214:217], v[0:3]
	s_setprio 0
	s_barrier
	ds_read_b128 v[128:131], v179
	ds_read_b128 v[132:135], v179 offset:1024
	ds_read_b128 v[152:155], v179 offset:2048
	ds_read_b128 v[156:159], v179 offset:3072
	ds_read_b128 v[160:163], v180
	ds_read_b128 v[164:167], v180 offset:1024
	ds_read_b128 v[168:171], v180 offset:2048
	ds_read_b128 v[182:185], v180 offset:3072
	s_add_u32 s24, s24, 0x160000
	s_addc_u32 s25, s25, 0
	s_mov_b32 m0, s30
	v_lshl_add_u64 v[224:225], s[24:25], 0, v[136:137]
	ds_read_b128 v[186:189], v178 offset:32768
	ds_read_b128 v[190:193], v178 offset:33792
	ds_read_b128 v[194:197], v178 offset:34816
	ds_read_b128 v[198:201], v178 offset:35840
	ds_read_b128 v[202:205], v178 offset:36864
	ds_read_b128 v[206:209], v178 offset:37888
	ds_read_b128 v[210:213], v178 offset:38912
	ds_read_b128 v[214:217], v178 offset:39936
	global_load_lds_dwordx4 v[224:225], off
	v_lshl_add_u64 v[224:225], s[24:25], 0, v[140:141]
	s_mov_b32 m0, s31
	s_nop 0
	global_load_lds_dwordx4 v[224:225], off
	s_waitcnt vmcnt(8)
	s_waitcnt lgkmcnt(0)
	s_barrier
	s_setprio 1
	v_mfma_f32_16x16x32_bf16 v[124:127], v[128:131], v[186:189], v[124:127]
	v_mfma_f32_16x16x32_bf16 v[120:123], v[152:155], v[186:189], v[120:123]
	v_mfma_f32_16x16x32_bf16 v[116:119], v[128:131], v[194:197], v[116:119]
	v_mfma_f32_16x16x32_bf16 v[112:115], v[152:155], v[194:197], v[112:115]
	v_mfma_f32_16x16x32_bf16 v[108:111], v[128:131], v[202:205], v[108:111]
	v_mfma_f32_16x16x32_bf16 v[104:107], v[152:155], v[202:205], v[104:107]
	v_mfma_f32_16x16x32_bf16 v[100:103], v[128:131], v[210:213], v[100:103]
	v_mfma_f32_16x16x32_bf16 v[96:99], v[152:155], v[210:213], v[96:99]
	v_mfma_f32_16x16x32_bf16 v[124:127], v[132:135], v[190:193], v[124:127]
	v_mfma_f32_16x16x32_bf16 v[120:123], v[156:159], v[190:193], v[120:123]
	v_mfma_f32_16x16x32_bf16 v[116:119], v[132:135], v[198:201], v[116:119]
	v_mfma_f32_16x16x32_bf16 v[112:115], v[156:159], v[198:201], v[112:115]
	v_mfma_f32_16x16x32_bf16 v[108:111], v[132:135], v[206:209], v[108:111]
	v_mfma_f32_16x16x32_bf16 v[104:107], v[156:159], v[206:209], v[104:107]
	v_mfma_f32_16x16x32_bf16 v[100:103], v[132:135], v[214:217], v[100:103]
	v_mfma_f32_16x16x32_bf16 v[96:99], v[156:159], v[214:217], v[96:99]
	s_setprio 0
	s_setprio 1
	v_mfma_f32_16x16x32_bf16 v[68:71], v[160:163], v[186:189], v[68:71]
	v_mfma_f32_16x16x32_bf16 v[60:63], v[168:171], v[186:189], v[60:63]
	v_mfma_f32_16x16x32_bf16 v[52:55], v[160:163], v[194:197], v[52:55]
	v_mfma_f32_16x16x32_bf16 v[48:51], v[168:171], v[194:197], v[48:51]
	v_mfma_f32_16x16x32_bf16 v[44:47], v[160:163], v[202:205], v[44:47]
	v_mfma_f32_16x16x32_bf16 v[40:43], v[168:171], v[202:205], v[40:43]
	v_mfma_f32_16x16x32_bf16 v[36:39], v[160:163], v[210:213], v[36:39]
	v_mfma_f32_16x16x32_bf16 v[32:35], v[168:171], v[210:213], v[32:35]
	v_mfma_f32_16x16x32_bf16 v[68:71], v[164:167], v[190:193], v[68:71]
	v_mfma_f32_16x16x32_bf16 v[60:63], v[182:185], v[190:193], v[60:63]
	v_mfma_f32_16x16x32_bf16 v[52:55], v[164:167], v[198:201], v[52:55]
	v_mfma_f32_16x16x32_bf16 v[48:51], v[182:185], v[198:201], v[48:51]
	v_mfma_f32_16x16x32_bf16 v[44:47], v[164:167], v[206:209], v[44:47]
	v_mfma_f32_16x16x32_bf16 v[40:43], v[182:185], v[206:209], v[40:43]
	v_mfma_f32_16x16x32_bf16 v[36:39], v[164:167], v[214:217], v[36:39]
	v_mfma_f32_16x16x32_bf16 v[32:35], v[182:185], v[214:217], v[32:35]
	s_setprio 0
	s_barrier
; #define PG8_STAGE(bufoff, gbase, voff) do { _Pragma("unroll") for (int _i = 0; _i < 2; ++_i) \
;         __builtin_amdgcn_global_load_lds((const unsigned*)((const char*)(gbase) + (voff)[_i]), (LAS unsigned*)(lds + (bufoff) + ldsw + _i * 8192), 16, 0, 0); } while (0)
; #define PG8_LDA(dst, b, h) do { _Pragma("unroll") for (int m = 0; m < 4; ++m) _Pragma("unroll") for (int k = 0; k < 2; ++k) dst[m][k] = *(const LAS bf16x8*)(lds + PG8_SA(b, h) + aoff + m * 2048 + k * 1024); } while (0)
; #define PG8_MMA(ai, bj, At, Bt) do { __builtin_amdgcn_s_setprio(1); _Pragma("unroll") for (int m = 0; m < 4; ++m) _Pragma("unroll") for (int n = 0; n < 2; ++n) _Pragma("unroll") for (int k = 0; k < 2; ++k) \
;         acc[ai][bj][m][n] = __builtin_amdgcn_mfma_f32_16x16x32_bf16(Bt[n][k], At[m][k], acc[ai][bj][m][n], 0, 0, 0); __builtin_amdgcn_s_setprio(0); } while (0)
; #define PG8_WAIT_V(n) asm volatile("s_waitcnt vmcnt(" #n ")" ::: "memory")
; #define PG8_WAIT_L(n) asm volatile("s_waitcnt lgkmcnt(" #n ")" ::: "memory")
; #define PG8_BAR __builtin_amdgcn_s_barrier()
; #define PG8_SCHED __builtin_amdgcn_sched_barrier(0)
; template <class Epi, class Sched, bool ALIGN_EPI = false, bool SP2 = false>
; __device__ __forceinline__ void gemm_phase(LAS unsigned char* lds, const Gemm g, const Sched& S, const Epi& E) {
;     ...
;         for (int t = 0; t < nt; t += 2) {
;             const bool last = (t == nt - 2);
;     ...
;             PG8_LDA(At, 1, 1); PG8_STAGE(PG8_SB(1, 0), b3, voffB); PG8_STAGE(PG8_SB(1, 1), b3 + hstepB, voffB); PG8_STAGE(PG8_SA(1, 0), a3, voffA);
;             PG8_WAIT_V(8); PG8_WAIT_L(0); PG8_BAR; PG8_MMA(1, 0, At, B0); PG8_MMA(1, 1, At, B1); PG8_BAR; PG8_SCHED;
	s_add_i32 s24, s42, s27
	v_lshl_add_u64 v[172:173], v[172:173], 0, s[8:9]
	s_mov_b32 m0, s24
	ds_read_b128 v[186:189], v178 offset:49152
	ds_read_b128 v[190:193], v178 offset:50176
	ds_read_b128 v[194:197], v178 offset:51200
	ds_read_b128 v[198:201], v178 offset:52224
	ds_read_b128 v[202:205], v178 offset:53248
	ds_read_b128 v[206:209], v178 offset:54272
	ds_read_b128 v[210:213], v178 offset:55296
	ds_read_b128 v[214:217], v178 offset:56320
	global_load_lds_dwordx4 v[172:173], off
	s_add_i32 m0, s24, 0x2000
	s_add_u32 s22, s22, 0x160080
	v_lshl_add_u64 v[172:173], v[218:219], 0, s[8:9]
	s_addc_u32 s23, s23, 0
	s_add_i32 s24, s43, s27
	global_load_lds_dwordx4 v[172:173], off
	v_lshl_add_u64 v[172:173], s[22:23], 0, v[138:139]
	s_mov_b32 m0, s24
	s_nop 0
	global_load_lds_dwordx4 v[172:173], off
	v_lshl_add_u64 v[172:173], s[22:23], 0, v[142:143]
	s_add_i32 m0, s24, 0x2000
	s_nop 0
	global_load_lds_dwordx4 v[172:173], off
	v_lshl_add_u64 v[172:173], v[220:221], 0, s[8:9]
	s_mov_b32 m0, s36
	s_nop 0
	global_load_lds_dwordx4 v[172:173], off
	v_lshl_add_u64 v[172:173], v[222:223], 0, s[8:9]
	s_mov_b32 m0, s37
	s_nop 0
	global_load_lds_dwordx4 v[172:173], off
	s_waitcnt vmcnt(8)
	s_waitcnt lgkmcnt(0)
	s_barrier
	s_setprio 1
	v_mfma_f32_16x16x32_bf16 v[92:95], v[128:131], v[186:189], v[92:95]
	v_mfma_f32_16x16x32_bf16 v[88:91], v[152:155], v[186:189], v[88:91]
	v_mfma_f32_16x16x32_bf16 v[84:87], v[128:131], v[194:197], v[84:87]
	v_mfma_f32_16x16x32_bf16 v[80:83], v[152:155], v[194:197], v[80:83]
	v_mfma_f32_16x16x32_bf16 v[76:79], v[128:131], v[202:205], v[76:79]
	v_mfma_f32_16x16x32_bf16 v[72:75], v[152:155], v[202:205], v[72:75]
	v_mfma_f32_16x16x32_bf16 v[64:67], v[128:131], v[210:213], v[64:67]
	v_mfma_f32_16x16x32_bf16 v[56:59], v[152:155], v[210:213], v[56:59]
	v_mfma_f32_16x16x32_bf16 v[92:95], v[132:135], v[190:193], v[92:95]
	v_mfma_f32_16x16x32_bf16 v[88:91], v[156:159], v[190:193], v[88:91]
	v_mfma_f32_16x16x32_bf16 v[84:87], v[132:135], v[198:201], v[84:87]
	v_mfma_f32_16x16x32_bf16 v[80:83], v[156:159], v[198:201], v[80:83]
	v_mfma_f32_16x16x32_bf16 v[76:79], v[132:135], v[206:209], v[76:79]
	v_mfma_f32_16x16x32_bf16 v[72:75], v[156:159], v[206:209], v[72:75]
	v_mfma_f32_16x16x32_bf16 v[64:67], v[132:135], v[214:217], v[64:67]
	v_mfma_f32_16x16x32_bf16 v[56:59], v[156:159], v[214:217], v[56:59]
	s_setprio 0
	s_setprio 1
	v_mfma_f32_16x16x32_bf16 v[28:31], v[160:163], v[186:189], v[28:31]
	v_mfma_f32_16x16x32_bf16 v[24:27], v[168:171], v[186:189], v[24:27]
	v_mfma_f32_16x16x32_bf16 v[20:23], v[160:163], v[194:197], v[20:23]
	v_mfma_f32_16x16x32_bf16 v[16:19], v[168:171], v[194:197], v[16:19]
	v_mfma_f32_16x16x32_bf16 v[12:15], v[160:163], v[202:205], v[12:15]
	v_mfma_f32_16x16x32_bf16 v[8:11], v[168:171], v[202:205], v[8:11]
	v_mfma_f32_16x16x32_bf16 v[4:7], v[160:163], v[210:213], v[4:7]
	v_mfma_f32_16x16x32_bf16 v[0:3], v[168:171], v[210:213], v[0:3]
	v_mfma_f32_16x16x32_bf16 v[28:31], v[164:167], v[190:193], v[28:31]
	v_mfma_f32_16x16x32_bf16 v[24:27], v[182:185], v[190:193], v[24:27]
	v_mfma_f32_16x16x32_bf16 v[20:23], v[164:167], v[198:201], v[20:23]
	v_mfma_f32_16x16x32_bf16 v[16:19], v[182:185], v[198:201], v[16:19]
	v_mfma_f32_16x16x32_bf16 v[12:15], v[164:167], v[206:209], v[12:15]
	v_mfma_f32_16x16x32_bf16 v[8:11], v[182:185], v[206:209], v[8:11]
	v_mfma_f32_16x16x32_bf16 v[4:7], v[164:167], v[214:217], v[4:7]
	v_mfma_f32_16x16x32_bf16 v[0:3], v[182:185], v[214:217], v[0:3]
	s_setprio 0
	s_barrier
	s_add_i32 s49, s49, 2
	s_add_u32 s20, s20, 0x100
	s_addc_u32 s21, s21, 0
	s_add_u32 s47, s47, 0x100
	s_addc_u32 s48, s48, 0
	s_cmpk_gt_u32 s49, 0x55
	s_cbranch_scc0 .LBB0_1138
	s_and_b64 vcc, exec, s[10:11]
	s_cbranch_vccz .LBB0_1141
	s_barrier
